# v17 + de-serialized f32 residual epilogues (all 16 residual loads first, then fmac, then 32 global stores)
# speedup vs baseline: 1.0111x; 1.0111x over previous
; __device__ __forceinline__ float bflo(unsigned w) { return __uint_as_float(w << 16); }
; __device__ __forceinline__ float bfhi(unsigned w) { return __uint_as_float(w & 0xffff0000u); }
;     __device__ __forceinline__ void operator()(const pg8::f32x4 (&acc)[2][2][4][2], const pg8::Unit& u, int wr, int wc, int fr, int fq) const {
;         const int row0 = u.pm * 256 + wr * 64 + fr, col0 = u.pn * 256 + wc * 32 + 8 * fq;
; #pragma unroll
;         for (int ai = 0; ai < 2; ++ai)
; #pragma unroll
;             for (int m = 0; m < 4; ++m) { const int row = row0 + ai * 128 + m * 16;
;                 float* zr = Z + (size_t)(row + (MODE == 0 ? NMETA : 0)) * DM;
;                 const bf16_t* hr = H + (size_t)(row + NMETA) * DM;
; #pragma unroll
;                 for (int bj = 0; bj < 2; ++bj) { const int c = col0 + bj * 128; const u32x4 hw = *(const u32x4*)(hr + c);
;                     pg8::f32x4 a0 = acc[ai][bj][m][0], a1 = acc[ai][bj][m][1];
;                     a0[0] += ALPHA * bflo(hw.x); a0[1] += ALPHA * bfhi(hw.x); a0[2] += ALPHA * bflo(hw.y); a0[3] += ALPHA * bfhi(hw.y);
;                     a1[0] += ALPHA * bflo(hw.z); a1[1] += ALPHA * bfhi(hw.z); a1[2] += ALPHA * bflo(hw.w); a1[3] += ALPHA * bfhi(hw.w);
;                     *(pg8::f32x4*)(zr + c) = a0; *(pg8::f32x4*)(zr + c + 4) = a1; } }
.LBB0_1132:
	v_lshl_add_u32 v148, s30, 8, v1
	v_lshl_or_b32 v146, s53, 8, v152
	v_lshlrev_b32_e32 v220, 12, v148
	v_lshl_add_u32 v220, v146, 1, v220
	v_lshlrev_b32_e32 v221, 13, v148
	v_lshl_add_u32 v221, v146, 2, v221
	s_andn2_b64 vcc, exec, s[6:7]
	s_mov_b64 s[6:7], -1
	s_mov_b64 s[98:99], s[10:11]
	global_load_dwordx4 v[146:149], v220, s[98:99]
	global_load_dwordx4 v[158:161], v220, s[98:99] offset:256
	s_add_u32 s98, s98, 0x10000
	s_addc_u32 s99, s99, 0
	global_load_dwordx4 v[162:165], v220, s[98:99]
	global_load_dwordx4 v[166:169], v220, s[98:99] offset:256
	s_add_u32 s98, s98, 0x10000
	s_addc_u32 s99, s99, 0
	global_load_dwordx4 v[170:173], v220, s[98:99]
	global_load_dwordx4 v[174:177], v220, s[98:99] offset:256
	s_add_u32 s98, s98, 0x10000
	s_addc_u32 s99, s99, 0
	global_load_dwordx4 v[178:181], v220, s[98:99]
	global_load_dwordx4 v[182:185], v220, s[98:99] offset:256
	s_add_u32 s98, s98, 0x50000
	s_addc_u32 s99, s99, 0
	global_load_dwordx4 v[186:189], v220, s[98:99]
	global_load_dwordx4 v[190:193], v220, s[98:99] offset:256
	s_add_u32 s98, s98, 0x10000
	s_addc_u32 s99, s99, 0
	global_load_dwordx4 v[196:199], v220, s[98:99]
	global_load_dwordx4 v[200:203], v220, s[98:99] offset:256
	s_add_u32 s98, s98, 0x10000
	s_addc_u32 s99, s99, 0
	global_load_dwordx4 v[204:207], v220, s[98:99]
	global_load_dwordx4 v[208:211], v220, s[98:99] offset:256
	s_add_u32 s98, s98, 0x10000
	s_addc_u32 s99, s99, 0
	global_load_dwordx4 v[212:215], v220, s[98:99]
	global_load_dwordx4 v[216:219], v220, s[98:99] offset:256
	s_mov_b64 s[100:101], s[12:13]
	s_waitcnt vmcnt(15)
	v_lshlrev_b32_e32 v222, 16, v146
	v_and_b32_e32 v146, 0xffff0000, v146
	v_fmac_f32_e32 v126, s20, v222
	v_fmac_f32_e32 v127, s20, v146
	v_lshlrev_b32_e32 v223, 16, v147
	v_and_b32_e32 v147, 0xffff0000, v147
	v_fmac_f32_e32 v128, s20, v223
	v_fmac_f32_e32 v129, s20, v147
	v_lshlrev_b32_e32 v222, 16, v148
	v_and_b32_e32 v148, 0xffff0000, v148
	v_fmac_f32_e32 v122, s20, v222
	v_fmac_f32_e32 v123, s20, v148
	v_lshlrev_b32_e32 v223, 16, v149
	v_and_b32_e32 v149, 0xffff0000, v149
	v_fmac_f32_e32 v124, s20, v223
	v_fmac_f32_e32 v125, s20, v149
	s_waitcnt vmcnt(14)
	v_lshlrev_b32_e32 v222, 16, v158
	v_and_b32_e32 v158, 0xffff0000, v158
	v_fmac_f32_e32 v118, s20, v222
	v_fmac_f32_e32 v119, s20, v158
	v_lshlrev_b32_e32 v223, 16, v159
	v_and_b32_e32 v159, 0xffff0000, v159
	v_fmac_f32_e32 v120, s20, v223
	v_fmac_f32_e32 v121, s20, v159
	v_lshlrev_b32_e32 v222, 16, v160
	v_and_b32_e32 v160, 0xffff0000, v160
	v_fmac_f32_e32 v114, s20, v222
	v_fmac_f32_e32 v115, s20, v160
	v_lshlrev_b32_e32 v223, 16, v161
	v_and_b32_e32 v161, 0xffff0000, v161
	v_fmac_f32_e32 v116, s20, v223
	v_fmac_f32_e32 v117, s20, v161
	s_waitcnt vmcnt(13)
	v_lshlrev_b32_e32 v222, 16, v162
	v_and_b32_e32 v162, 0xffff0000, v162
	v_fmac_f32_e32 v110, s20, v222
	v_fmac_f32_e32 v111, s20, v162
	v_lshlrev_b32_e32 v223, 16, v163
	v_and_b32_e32 v163, 0xffff0000, v163
	v_fmac_f32_e32 v112, s20, v223
	v_fmac_f32_e32 v113, s20, v163
	v_lshlrev_b32_e32 v222, 16, v164
	v_and_b32_e32 v164, 0xffff0000, v164
	v_fmac_f32_e32 v106, s20, v222
	v_fmac_f32_e32 v107, s20, v164
	v_lshlrev_b32_e32 v223, 16, v165
	v_and_b32_e32 v165, 0xffff0000, v165
	v_fmac_f32_e32 v108, s20, v223
	v_fmac_f32_e32 v109, s20, v165
	s_waitcnt vmcnt(12)
	v_lshlrev_b32_e32 v222, 16, v166
	v_and_b32_e32 v166, 0xffff0000, v166
	v_fmac_f32_e32 v102, s20, v222
	v_fmac_f32_e32 v103, s20, v166
	v_lshlrev_b32_e32 v223, 16, v167
	v_and_b32_e32 v167, 0xffff0000, v167
	v_fmac_f32_e32 v104, s20, v223
	v_fmac_f32_e32 v105, s20, v167
	v_lshlrev_b32_e32 v222, 16, v168
	v_and_b32_e32 v168, 0xffff0000, v168
	v_fmac_f32_e32 v98, s20, v222
	v_fmac_f32_e32 v99, s20, v168
	v_lshlrev_b32_e32 v223, 16, v169
	v_and_b32_e32 v169, 0xffff0000, v169
	v_fmac_f32_e32 v100, s20, v223
	v_fmac_f32_e32 v101, s20, v169
	s_waitcnt vmcnt(11)
	v_lshlrev_b32_e32 v222, 16, v170
	v_and_b32_e32 v170, 0xffff0000, v170
	v_fmac_f32_e32 v94, s20, v222
	v_fmac_f32_e32 v95, s20, v170
	v_lshlrev_b32_e32 v223, 16, v171
	v_and_b32_e32 v171, 0xffff0000, v171
	v_fmac_f32_e32 v96, s20, v223
	v_fmac_f32_e32 v97, s20, v171
	v_lshlrev_b32_e32 v222, 16, v172
	v_and_b32_e32 v172, 0xffff0000, v172
	v_fmac_f32_e32 v90, s20, v222
	v_fmac_f32_e32 v91, s20, v172
	v_lshlrev_b32_e32 v223, 16, v173
	v_and_b32_e32 v173, 0xffff0000, v173
	v_fmac_f32_e32 v92, s20, v223
	v_fmac_f32_e32 v93, s20, v173
	s_waitcnt vmcnt(10)
	v_lshlrev_b32_e32 v222, 16, v174
	v_and_b32_e32 v174, 0xffff0000, v174
	v_fmac_f32_e32 v86, s20, v222
	v_fmac_f32_e32 v87, s20, v174
	v_lshlrev_b32_e32 v223, 16, v175
	v_and_b32_e32 v175, 0xffff0000, v175
	v_fmac_f32_e32 v88, s20, v223
	v_fmac_f32_e32 v89, s20, v175
	v_lshlrev_b32_e32 v222, 16, v176
	v_and_b32_e32 v176, 0xffff0000, v176
	v_fmac_f32_e32 v82, s20, v222
	v_fmac_f32_e32 v83, s20, v176
	v_lshlrev_b32_e32 v223, 16, v177
	v_and_b32_e32 v177, 0xffff0000, v177
	v_fmac_f32_e32 v84, s20, v223
	v_fmac_f32_e32 v85, s20, v177
	s_waitcnt vmcnt(9)
	v_lshlrev_b32_e32 v222, 16, v178
	v_and_b32_e32 v178, 0xffff0000, v178
	v_fmac_f32_e32 v78, s20, v222
	v_fmac_f32_e32 v79, s20, v178
	v_lshlrev_b32_e32 v223, 16, v179
	v_and_b32_e32 v179, 0xffff0000, v179
	v_fmac_f32_e32 v80, s20, v223
	v_fmac_f32_e32 v81, s20, v179
	v_lshlrev_b32_e32 v222, 16, v180
	v_and_b32_e32 v180, 0xffff0000, v180
	v_fmac_f32_e32 v74, s20, v222
	v_fmac_f32_e32 v75, s20, v180
	v_lshlrev_b32_e32 v223, 16, v181
	v_and_b32_e32 v181, 0xffff0000, v181
	v_fmac_f32_e32 v76, s20, v223
	v_fmac_f32_e32 v77, s20, v181
	s_waitcnt vmcnt(8)
; __device__ __forceinline__ float bflo(unsigned w) { return __uint_as_float(w << 16); }
; __device__ __forceinline__ float bfhi(unsigned w) { return __uint_as_float(w & 0xffff0000u); }
;     __device__ __forceinline__ void operator()(const pg8::f32x4 (&acc)[2][2][4][2], const pg8::Unit& u, int wr, int wc, int fr, int fq) const {
;     ...
;                 for (int bj = 0; bj < 2; ++bj) { const int c = col0 + bj * 128; const u32x4 hw = *(const u32x4*)(hr + c);
;                     pg8::f32x4 a0 = acc[ai][bj][m][0], a1 = acc[ai][bj][m][1];
;                     a0[0] += ALPHA * bflo(hw.x); a0[1] += ALPHA * bfhi(hw.x); a0[2] += ALPHA * bflo(hw.y); a0[3] += ALPHA * bfhi(hw.y);
;                     a1[0] += ALPHA * bflo(hw.z); a1[1] += ALPHA * bfhi(hw.z); a1[2] += ALPHA * bflo(hw.w); a1[3] += ALPHA * bfhi(hw.w);
	v_lshlrev_b32_e32 v222, 16, v182
	v_and_b32_e32 v182, 0xffff0000, v182
	v_fmac_f32_e32 v70, s20, v222
	v_fmac_f32_e32 v71, s20, v182
	v_lshlrev_b32_e32 v223, 16, v183
	v_and_b32_e32 v183, 0xffff0000, v183
	v_fmac_f32_e32 v72, s20, v223
	v_fmac_f32_e32 v73, s20, v183
	v_lshlrev_b32_e32 v222, 16, v184
	v_and_b32_e32 v184, 0xffff0000, v184
	v_fmac_f32_e32 v66, s20, v222
	v_fmac_f32_e32 v67, s20, v184
	v_lshlrev_b32_e32 v223, 16, v185
	v_and_b32_e32 v185, 0xffff0000, v185
	v_fmac_f32_e32 v68, s20, v223
	v_fmac_f32_e32 v69, s20, v185
	s_waitcnt vmcnt(7)
	v_lshlrev_b32_e32 v222, 16, v186
	v_and_b32_e32 v186, 0xffff0000, v186
	v_fmac_f32_e32 v62, s20, v222
	v_fmac_f32_e32 v63, s20, v186
	v_lshlrev_b32_e32 v223, 16, v187
	v_and_b32_e32 v187, 0xffff0000, v187
	v_fmac_f32_e32 v64, s20, v223
	v_fmac_f32_e32 v65, s20, v187
	v_lshlrev_b32_e32 v222, 16, v188
	v_and_b32_e32 v188, 0xffff0000, v188
	v_fmac_f32_e32 v58, s20, v222
	v_fmac_f32_e32 v59, s20, v188
	v_lshlrev_b32_e32 v223, 16, v189
	v_and_b32_e32 v189, 0xffff0000, v189
	v_fmac_f32_e32 v60, s20, v223
	v_fmac_f32_e32 v61, s20, v189
	s_waitcnt vmcnt(6)
	v_lshlrev_b32_e32 v222, 16, v190
	v_and_b32_e32 v190, 0xffff0000, v190
	v_fmac_f32_e32 v54, s20, v222
	v_fmac_f32_e32 v55, s20, v190
	v_lshlrev_b32_e32 v223, 16, v191
	v_and_b32_e32 v191, 0xffff0000, v191
	v_fmac_f32_e32 v56, s20, v223
	v_fmac_f32_e32 v57, s20, v191
	v_lshlrev_b32_e32 v222, 16, v192
	v_and_b32_e32 v192, 0xffff0000, v192
	v_fmac_f32_e32 v50, s20, v222
	v_fmac_f32_e32 v51, s20, v192
	v_lshlrev_b32_e32 v223, 16, v193
	v_and_b32_e32 v193, 0xffff0000, v193
	v_fmac_f32_e32 v52, s20, v223
	v_fmac_f32_e32 v53, s20, v193
	s_waitcnt vmcnt(5)
	v_lshlrev_b32_e32 v222, 16, v196
	v_and_b32_e32 v196, 0xffff0000, v196
	v_fmac_f32_e32 v46, s20, v222
	v_fmac_f32_e32 v47, s20, v196
	v_lshlrev_b32_e32 v223, 16, v197
	v_and_b32_e32 v197, 0xffff0000, v197
	v_fmac_f32_e32 v48, s20, v223
	v_fmac_f32_e32 v49, s20, v197
	v_lshlrev_b32_e32 v222, 16, v198
	v_and_b32_e32 v198, 0xffff0000, v198
	v_fmac_f32_e32 v42, s20, v222
	v_fmac_f32_e32 v43, s20, v198
	v_lshlrev_b32_e32 v223, 16, v199
	v_and_b32_e32 v199, 0xffff0000, v199
	v_fmac_f32_e32 v44, s20, v223
	v_fmac_f32_e32 v45, s20, v199
	s_waitcnt vmcnt(4)
	v_lshlrev_b32_e32 v222, 16, v200
	v_and_b32_e32 v200, 0xffff0000, v200
	v_fmac_f32_e32 v38, s20, v222
	v_fmac_f32_e32 v39, s20, v200
	v_lshlrev_b32_e32 v223, 16, v201
	v_and_b32_e32 v201, 0xffff0000, v201
	v_fmac_f32_e32 v40, s20, v223
	v_fmac_f32_e32 v41, s20, v201
	v_lshlrev_b32_e32 v222, 16, v202
	v_and_b32_e32 v202, 0xffff0000, v202
	v_fmac_f32_e32 v34, s20, v222
	v_fmac_f32_e32 v35, s20, v202
	v_lshlrev_b32_e32 v223, 16, v203
	v_and_b32_e32 v203, 0xffff0000, v203
	v_fmac_f32_e32 v36, s20, v223
	v_fmac_f32_e32 v37, s20, v203
	s_waitcnt vmcnt(3)
	v_lshlrev_b32_e32 v222, 16, v204
	v_and_b32_e32 v204, 0xffff0000, v204
	v_fmac_f32_e32 v30, s20, v222
	v_fmac_f32_e32 v31, s20, v204
	v_lshlrev_b32_e32 v223, 16, v205
	v_and_b32_e32 v205, 0xffff0000, v205
	v_fmac_f32_e32 v32, s20, v223
	v_fmac_f32_e32 v33, s20, v205
	v_lshlrev_b32_e32 v222, 16, v206
	v_and_b32_e32 v206, 0xffff0000, v206
	v_fmac_f32_e32 v26, s20, v222
	v_fmac_f32_e32 v27, s20, v206
	v_lshlrev_b32_e32 v223, 16, v207
	v_and_b32_e32 v207, 0xffff0000, v207
	v_fmac_f32_e32 v28, s20, v223
	v_fmac_f32_e32 v29, s20, v207
	s_waitcnt vmcnt(2)
	v_lshlrev_b32_e32 v222, 16, v208
	v_and_b32_e32 v208, 0xffff0000, v208
	v_fmac_f32_e32 v22, s20, v222
	v_fmac_f32_e32 v23, s20, v208
	v_lshlrev_b32_e32 v223, 16, v209
	v_and_b32_e32 v209, 0xffff0000, v209
	v_fmac_f32_e32 v24, s20, v223
	v_fmac_f32_e32 v25, s20, v209
	v_lshlrev_b32_e32 v222, 16, v210
	v_and_b32_e32 v210, 0xffff0000, v210
	v_fmac_f32_e32 v18, s20, v222
	v_fmac_f32_e32 v19, s20, v210
	v_lshlrev_b32_e32 v223, 16, v211
	v_and_b32_e32 v211, 0xffff0000, v211
	v_fmac_f32_e32 v20, s20, v223
	v_fmac_f32_e32 v21, s20, v211
	s_waitcnt vmcnt(1)
; #define PG8_BAR __builtin_amdgcn_s_barrier()
; __device__ __forceinline__ float bflo(unsigned w) { return __uint_as_float(w << 16); }
; __device__ __forceinline__ float bfhi(unsigned w) { return __uint_as_float(w & 0xffff0000u); }
; template <class Epi, class Sched, bool ALIGN_EPI = false, bool SP2 = false>
; __device__ __forceinline__ void gemm_phase(PG8_LAS unsigned char* lds, const Gemm g, const Sched& S, const Epi& E) {
;     ...
;         if constexpr (!Epi::AFTER_DRAIN) { E(acc, cur, wr, wc, fr, fq); S.done(cur); }
;         if (!has_next) break;
; #pragma unroll
;         for (int a = 0; a < 2; ++a)
; #pragma unroll
;             for (int b = 0; b < 2; ++b)
; #pragma unroll
;                 for (int m = 0; m < 4; ++m)
; #pragma unroll
;                     for (int n = 0; n < 2; ++n) acc[a][b][m][n] = (f32x4){0.f, 0.f, 0.f, 0.f};
;         cur = nxt; cA = nA; cB = nB; ++ui;
;         if constexpr (ALIGN_EPI) { if (wr == 1) PG8_BAR; }
;     __device__ __forceinline__ void operator()(const pg8::f32x4 (&acc)[2][2][4][2], const pg8::Unit& u, int wr, int wc, int fr, int fq) const {
;     ...
;                     a0[0] += ALPHA * bflo(hw.x); a0[1] += ALPHA * bfhi(hw.x); a0[2] += ALPHA * bflo(hw.y); a0[3] += ALPHA * bfhi(hw.y);
;                     a1[0] += ALPHA * bflo(hw.z); a1[1] += ALPHA * bfhi(hw.z); a1[2] += ALPHA * bflo(hw.w); a1[3] += ALPHA * bfhi(hw.w);
;                     *(pg8::f32x4*)(zr + c) = a0; *(pg8::f32x4*)(zr + c + 4) = a1; } }
	v_lshlrev_b32_e32 v222, 16, v212
	v_and_b32_e32 v212, 0xffff0000, v212
	v_fmac_f32_e32 v14, s20, v222
	v_fmac_f32_e32 v15, s20, v212
	v_lshlrev_b32_e32 v223, 16, v213
	v_and_b32_e32 v213, 0xffff0000, v213
	v_fmac_f32_e32 v16, s20, v223
	v_fmac_f32_e32 v17, s20, v213
	v_lshlrev_b32_e32 v222, 16, v214
	v_and_b32_e32 v214, 0xffff0000, v214
	v_fmac_f32_e32 v10, s20, v222
	v_fmac_f32_e32 v11, s20, v214
	v_lshlrev_b32_e32 v223, 16, v215
	v_and_b32_e32 v215, 0xffff0000, v215
	v_fmac_f32_e32 v12, s20, v223
	v_fmac_f32_e32 v13, s20, v215
	s_waitcnt vmcnt(0)
	v_lshlrev_b32_e32 v222, 16, v216
	v_and_b32_e32 v216, 0xffff0000, v216
	v_fmac_f32_e32 v6, s20, v222
	v_fmac_f32_e32 v7, s20, v216
	v_lshlrev_b32_e32 v223, 16, v217
	v_and_b32_e32 v217, 0xffff0000, v217
	v_fmac_f32_e32 v8, s20, v223
	v_fmac_f32_e32 v9, s20, v217
	v_lshlrev_b32_e32 v222, 16, v218
	v_and_b32_e32 v218, 0xffff0000, v218
	v_fmac_f32_e32 v2, s20, v222
	v_fmac_f32_e32 v3, s20, v218
	v_lshlrev_b32_e32 v223, 16, v219
	v_and_b32_e32 v219, 0xffff0000, v219
	v_fmac_f32_e32 v4, s20, v223
	v_fmac_f32_e32 v5, s20, v219
	global_store_dwordx4 v221, v[126:129], s[100:101]
	global_store_dwordx4 v221, v[122:125], s[100:101] offset:16
	global_store_dwordx4 v221, v[118:121], s[100:101] offset:512
	global_store_dwordx4 v221, v[114:117], s[100:101] offset:528
	s_add_u32 s100, s100, 0x20000
	s_addc_u32 s101, s101, 0
	global_store_dwordx4 v221, v[110:113], s[100:101]
	global_store_dwordx4 v221, v[106:109], s[100:101] offset:16
	global_store_dwordx4 v221, v[102:105], s[100:101] offset:512
	global_store_dwordx4 v221, v[98:101], s[100:101] offset:528
	s_add_u32 s100, s100, 0x20000
	s_addc_u32 s101, s101, 0
	global_store_dwordx4 v221, v[94:97], s[100:101]
	global_store_dwordx4 v221, v[90:93], s[100:101] offset:16
	global_store_dwordx4 v221, v[86:89], s[100:101] offset:512
	global_store_dwordx4 v221, v[82:85], s[100:101] offset:528
	s_add_u32 s100, s100, 0x20000
	s_addc_u32 s101, s101, 0
	global_store_dwordx4 v221, v[78:81], s[100:101]
	global_store_dwordx4 v221, v[74:77], s[100:101] offset:16
	global_store_dwordx4 v221, v[70:73], s[100:101] offset:512
	global_store_dwordx4 v221, v[66:69], s[100:101] offset:528
	s_add_u32 s100, s100, 0xa0000
	s_addc_u32 s101, s101, 0
	global_store_dwordx4 v221, v[62:65], s[100:101]
	global_store_dwordx4 v221, v[58:61], s[100:101] offset:16
	global_store_dwordx4 v221, v[54:57], s[100:101] offset:512
	global_store_dwordx4 v221, v[50:53], s[100:101] offset:528
	s_add_u32 s100, s100, 0x20000
	s_addc_u32 s101, s101, 0
	global_store_dwordx4 v221, v[46:49], s[100:101]
	global_store_dwordx4 v221, v[42:45], s[100:101] offset:16
	global_store_dwordx4 v221, v[38:41], s[100:101] offset:512
	global_store_dwordx4 v221, v[34:37], s[100:101] offset:528
	s_add_u32 s100, s100, 0x20000
	s_addc_u32 s101, s101, 0
	global_store_dwordx4 v221, v[30:33], s[100:101]
	global_store_dwordx4 v221, v[26:29], s[100:101] offset:16
	global_store_dwordx4 v221, v[22:25], s[100:101] offset:512
	global_store_dwordx4 v221, v[18:21], s[100:101] offset:528
	s_add_u32 s100, s100, 0x20000
	s_addc_u32 s101, s101, 0
	global_store_dwordx4 v221, v[14:17], s[100:101]
	global_store_dwordx4 v221, v[10:13], s[100:101] offset:16
	global_store_dwordx4 v221, v[6:9], s[100:101] offset:512
	global_store_dwordx4 v221, v[2:5], s[100:101] offset:528
	s_cbranch_vccnz .LBB0_1121
	s_andn2_b64 vcc, exec, s[14:15]
	s_cbranch_vccnz .LBB0_1120
	s_barrier
	s_branch .LBB0_1120

; __device__ __forceinline__ float bflo(unsigned w) { return __uint_as_float(w << 16); }
; __device__ __forceinline__ float bfhi(unsigned w) { return __uint_as_float(w & 0xffff0000u); }
;     __device__ __forceinline__ void operator()(const pg8::f32x4 (&acc)[2][2][4][2], const pg8::Unit& u, int wr, int wc, int fr, int fq) const {
;         const int row0 = u.pm * 256 + wr * 64 + fr, col0 = u.pn * 256 + wc * 32 + 8 * fq;
; #pragma unroll
;         for (int ai = 0; ai < 2; ++ai)
; #pragma unroll
;             for (int m = 0; m < 4; ++m) { const int row = row0 + ai * 128 + m * 16;
;                 float* zr = Z + (size_t)(row + (MODE == 0 ? NMETA : 0)) * DM;
;                 const bf16_t* hr = H + (size_t)(row + NMETA) * DM;
; #pragma unroll
;                 for (int bj = 0; bj < 2; ++bj) { const int c = col0 + bj * 128; const u32x4 hw = *(const u32x4*)(hr + c);
;                     pg8::f32x4 a0 = acc[ai][bj][m][0], a1 = acc[ai][bj][m][1];
;                     a0[0] += ALPHA * bflo(hw.x); a0[1] += ALPHA * bfhi(hw.x); a0[2] += ALPHA * bflo(hw.y); a0[3] += ALPHA * bfhi(hw.y);
;                     a1[0] += ALPHA * bflo(hw.z); a1[1] += ALPHA * bfhi(hw.z); a1[2] += ALPHA * bflo(hw.w); a1[3] += ALPHA * bfhi(hw.w);
;                     *(pg8::f32x4*)(zr + c) = a0; *(pg8::f32x4*)(zr + c + 4) = a1; } }
.LBB0_1386:
	v_lshl_add_u32 v148, s40, 8, v1
	v_or_b32_e32 v164, 16, v148
	v_lshl_or_b32 v146, s62, 8, v154
	v_lshlrev_b32_e32 v220, 12, v164
	v_lshl_add_u32 v220, v146, 1, v220
	v_lshlrev_b32_e32 v221, 13, v148
	v_lshl_add_u32 v221, v146, 2, v221
	s_nop 0
	s_andn2_b64 vcc, exec, s[6:7]
	s_mov_b64 s[6:7], -1
	s_mov_b64 s[98:99], s[14:15]
	global_load_dwordx4 v[146:149], v220, s[98:99]
	global_load_dwordx4 v[150:153], v220, s[98:99] offset:256
	s_add_u32 s98, s98, 0x10000
	s_addc_u32 s99, s99, 0
	global_load_dwordx4 v[160:163], v220, s[98:99]
	global_load_dwordx4 v[164:167], v220, s[98:99] offset:256
	s_add_u32 s98, s98, 0x10000
	s_addc_u32 s99, s99, 0
	global_load_dwordx4 v[168:171], v220, s[98:99]
	global_load_dwordx4 v[172:175], v220, s[98:99] offset:256
	s_add_u32 s98, s98, 0x10000
	s_addc_u32 s99, s99, 0
	global_load_dwordx4 v[176:179], v220, s[98:99]
	global_load_dwordx4 v[180:183], v220, s[98:99] offset:256
	s_add_u32 s98, s98, 0x50000
	s_addc_u32 s99, s99, 0
	global_load_dwordx4 v[184:187], v220, s[98:99]
	global_load_dwordx4 v[188:191], v220, s[98:99] offset:256
	s_add_u32 s98, s98, 0x10000
	s_addc_u32 s99, s99, 0
	global_load_dwordx4 v[196:199], v220, s[98:99]
	global_load_dwordx4 v[200:203], v220, s[98:99] offset:256
	s_add_u32 s98, s98, 0x10000
	s_addc_u32 s99, s99, 0
	global_load_dwordx4 v[204:207], v220, s[98:99]
	global_load_dwordx4 v[208:211], v220, s[98:99] offset:256
	s_add_u32 s98, s98, 0x10000
	s_addc_u32 s99, s99, 0
	global_load_dwordx4 v[212:215], v220, s[98:99]
	global_load_dwordx4 v[216:219], v220, s[98:99] offset:256
	s_mov_b64 s[100:101], s[8:9]
	s_waitcnt vmcnt(15)
	v_lshlrev_b32_e32 v222, 16, v146
	v_and_b32_e32 v146, 0xffff0000, v146
	v_fmac_f32_e32 v126, s20, v222
	v_fmac_f32_e32 v127, s20, v146
	v_lshlrev_b32_e32 v223, 16, v147
	v_and_b32_e32 v147, 0xffff0000, v147
	v_fmac_f32_e32 v128, s20, v223
	v_fmac_f32_e32 v129, s20, v147
	v_lshlrev_b32_e32 v222, 16, v148
	v_and_b32_e32 v148, 0xffff0000, v148
	v_fmac_f32_e32 v122, s20, v222
	v_fmac_f32_e32 v123, s20, v148
	v_lshlrev_b32_e32 v223, 16, v149
	v_and_b32_e32 v149, 0xffff0000, v149
	v_fmac_f32_e32 v124, s20, v223
	v_fmac_f32_e32 v125, s20, v149
	s_waitcnt vmcnt(14)
	v_lshlrev_b32_e32 v222, 16, v150
	v_and_b32_e32 v150, 0xffff0000, v150
	v_fmac_f32_e32 v118, s20, v222
	v_fmac_f32_e32 v119, s20, v150
	v_lshlrev_b32_e32 v223, 16, v151
	v_and_b32_e32 v151, 0xffff0000, v151
	v_fmac_f32_e32 v120, s20, v223
	v_fmac_f32_e32 v121, s20, v151
	v_lshlrev_b32_e32 v222, 16, v152
	v_and_b32_e32 v152, 0xffff0000, v152
	v_fmac_f32_e32 v114, s20, v222
	v_fmac_f32_e32 v115, s20, v152
	v_lshlrev_b32_e32 v223, 16, v153
	v_and_b32_e32 v153, 0xffff0000, v153
	v_fmac_f32_e32 v116, s20, v223
	v_fmac_f32_e32 v117, s20, v153
	s_waitcnt vmcnt(13)
	v_lshlrev_b32_e32 v222, 16, v160
	v_and_b32_e32 v160, 0xffff0000, v160
	v_fmac_f32_e32 v110, s20, v222
	v_fmac_f32_e32 v111, s20, v160
	v_lshlrev_b32_e32 v223, 16, v161
	v_and_b32_e32 v161, 0xffff0000, v161
	v_fmac_f32_e32 v112, s20, v223
	v_fmac_f32_e32 v113, s20, v161
	v_lshlrev_b32_e32 v222, 16, v162
	v_and_b32_e32 v162, 0xffff0000, v162
	v_fmac_f32_e32 v106, s20, v222
	v_fmac_f32_e32 v107, s20, v162
	v_lshlrev_b32_e32 v223, 16, v163
	v_and_b32_e32 v163, 0xffff0000, v163
	v_fmac_f32_e32 v108, s20, v223
	v_fmac_f32_e32 v109, s20, v163
	s_waitcnt vmcnt(12)
	v_lshlrev_b32_e32 v222, 16, v164
	v_and_b32_e32 v164, 0xffff0000, v164
	v_fmac_f32_e32 v102, s20, v222
	v_fmac_f32_e32 v103, s20, v164
	v_lshlrev_b32_e32 v223, 16, v165
	v_and_b32_e32 v165, 0xffff0000, v165
	v_fmac_f32_e32 v104, s20, v223
	v_fmac_f32_e32 v105, s20, v165
	v_lshlrev_b32_e32 v222, 16, v166
	v_and_b32_e32 v166, 0xffff0000, v166
	v_fmac_f32_e32 v98, s20, v222
	v_fmac_f32_e32 v99, s20, v166
	v_lshlrev_b32_e32 v223, 16, v167
	v_and_b32_e32 v167, 0xffff0000, v167
	v_fmac_f32_e32 v100, s20, v223
	v_fmac_f32_e32 v101, s20, v167
	s_waitcnt vmcnt(11)
	v_lshlrev_b32_e32 v222, 16, v168
	v_and_b32_e32 v168, 0xffff0000, v168
	v_fmac_f32_e32 v94, s20, v222
	v_fmac_f32_e32 v95, s20, v168
	v_lshlrev_b32_e32 v223, 16, v169
	v_and_b32_e32 v169, 0xffff0000, v169
	v_fmac_f32_e32 v96, s20, v223
	v_fmac_f32_e32 v97, s20, v169
	v_lshlrev_b32_e32 v222, 16, v170
	v_and_b32_e32 v170, 0xffff0000, v170
	v_fmac_f32_e32 v90, s20, v222
	v_fmac_f32_e32 v91, s20, v170
	v_lshlrev_b32_e32 v223, 16, v171
	v_and_b32_e32 v171, 0xffff0000, v171
	v_fmac_f32_e32 v92, s20, v223
	v_fmac_f32_e32 v93, s20, v171
	s_waitcnt vmcnt(10)
	v_lshlrev_b32_e32 v222, 16, v172
	v_and_b32_e32 v172, 0xffff0000, v172
	v_fmac_f32_e32 v86, s20, v222
	v_fmac_f32_e32 v87, s20, v172
	v_lshlrev_b32_e32 v223, 16, v173
	v_and_b32_e32 v173, 0xffff0000, v173
	v_fmac_f32_e32 v88, s20, v223
	v_fmac_f32_e32 v89, s20, v173
	v_lshlrev_b32_e32 v222, 16, v174
	v_and_b32_e32 v174, 0xffff0000, v174
	v_fmac_f32_e32 v82, s20, v222
	v_fmac_f32_e32 v83, s20, v174
	v_lshlrev_b32_e32 v223, 16, v175
	v_and_b32_e32 v175, 0xffff0000, v175
	v_fmac_f32_e32 v84, s20, v223
	v_fmac_f32_e32 v85, s20, v175
	s_waitcnt vmcnt(9)
	v_lshlrev_b32_e32 v222, 16, v176
	v_and_b32_e32 v176, 0xffff0000, v176
	v_fmac_f32_e32 v78, s20, v222
	v_fmac_f32_e32 v79, s20, v176
	v_lshlrev_b32_e32 v223, 16, v177
	v_and_b32_e32 v177, 0xffff0000, v177
	v_fmac_f32_e32 v80, s20, v223
	v_fmac_f32_e32 v81, s20, v177
	v_lshlrev_b32_e32 v222, 16, v178
	v_and_b32_e32 v178, 0xffff0000, v178
	v_fmac_f32_e32 v74, s20, v222
	v_fmac_f32_e32 v75, s20, v178
	v_lshlrev_b32_e32 v223, 16, v179
	v_and_b32_e32 v179, 0xffff0000, v179
	v_fmac_f32_e32 v76, s20, v223
	v_fmac_f32_e32 v77, s20, v179
	s_waitcnt vmcnt(8)
; __device__ __forceinline__ float bflo(unsigned w) { return __uint_as_float(w << 16); }
; __device__ __forceinline__ float bfhi(unsigned w) { return __uint_as_float(w & 0xffff0000u); }
;     __device__ __forceinline__ void operator()(const pg8::f32x4 (&acc)[2][2][4][2], const pg8::Unit& u, int wr, int wc, int fr, int fq) const {
;     ...
;                 for (int bj = 0; bj < 2; ++bj) { const int c = col0 + bj * 128; const u32x4 hw = *(const u32x4*)(hr + c);
;                     pg8::f32x4 a0 = acc[ai][bj][m][0], a1 = acc[ai][bj][m][1];
;                     a0[0] += ALPHA * bflo(hw.x); a0[1] += ALPHA * bfhi(hw.x); a0[2] += ALPHA * bflo(hw.y); a0[3] += ALPHA * bfhi(hw.y);
;                     a1[0] += ALPHA * bflo(hw.z); a1[1] += ALPHA * bfhi(hw.z); a1[2] += ALPHA * bflo(hw.w); a1[3] += ALPHA * bfhi(hw.w);
	v_lshlrev_b32_e32 v222, 16, v180
	v_and_b32_e32 v180, 0xffff0000, v180
	v_fmac_f32_e32 v70, s20, v222
	v_fmac_f32_e32 v71, s20, v180
	v_lshlrev_b32_e32 v223, 16, v181
	v_and_b32_e32 v181, 0xffff0000, v181
	v_fmac_f32_e32 v72, s20, v223
	v_fmac_f32_e32 v73, s20, v181
	v_lshlrev_b32_e32 v222, 16, v182
	v_and_b32_e32 v182, 0xffff0000, v182
	v_fmac_f32_e32 v66, s20, v222
	v_fmac_f32_e32 v67, s20, v182
	v_lshlrev_b32_e32 v223, 16, v183
	v_and_b32_e32 v183, 0xffff0000, v183
	v_fmac_f32_e32 v68, s20, v223
	v_fmac_f32_e32 v69, s20, v183
	s_waitcnt vmcnt(7)
	v_lshlrev_b32_e32 v222, 16, v184
	v_and_b32_e32 v184, 0xffff0000, v184
	v_fmac_f32_e32 v62, s20, v222
	v_fmac_f32_e32 v63, s20, v184
	v_lshlrev_b32_e32 v223, 16, v185
	v_and_b32_e32 v185, 0xffff0000, v185
	v_fmac_f32_e32 v64, s20, v223
	v_fmac_f32_e32 v65, s20, v185
	v_lshlrev_b32_e32 v222, 16, v186
	v_and_b32_e32 v186, 0xffff0000, v186
	v_fmac_f32_e32 v58, s20, v222
	v_fmac_f32_e32 v59, s20, v186
	v_lshlrev_b32_e32 v223, 16, v187
	v_and_b32_e32 v187, 0xffff0000, v187
	v_fmac_f32_e32 v60, s20, v223
	v_fmac_f32_e32 v61, s20, v187
	s_waitcnt vmcnt(6)
	v_lshlrev_b32_e32 v222, 16, v188
	v_and_b32_e32 v188, 0xffff0000, v188
	v_fmac_f32_e32 v54, s20, v222
	v_fmac_f32_e32 v55, s20, v188
	v_lshlrev_b32_e32 v223, 16, v189
	v_and_b32_e32 v189, 0xffff0000, v189
	v_fmac_f32_e32 v56, s20, v223
	v_fmac_f32_e32 v57, s20, v189
	v_lshlrev_b32_e32 v222, 16, v190
	v_and_b32_e32 v190, 0xffff0000, v190
	v_fmac_f32_e32 v50, s20, v222
	v_fmac_f32_e32 v51, s20, v190
	v_lshlrev_b32_e32 v223, 16, v191
	v_and_b32_e32 v191, 0xffff0000, v191
	v_fmac_f32_e32 v52, s20, v223
	v_fmac_f32_e32 v53, s20, v191
	s_waitcnt vmcnt(5)
	v_lshlrev_b32_e32 v222, 16, v196
	v_and_b32_e32 v196, 0xffff0000, v196
	v_fmac_f32_e32 v46, s20, v222
	v_fmac_f32_e32 v47, s20, v196
	v_lshlrev_b32_e32 v223, 16, v197
	v_and_b32_e32 v197, 0xffff0000, v197
	v_fmac_f32_e32 v48, s20, v223
	v_fmac_f32_e32 v49, s20, v197
	v_lshlrev_b32_e32 v222, 16, v198
	v_and_b32_e32 v198, 0xffff0000, v198
	v_fmac_f32_e32 v42, s20, v222
	v_fmac_f32_e32 v43, s20, v198
	v_lshlrev_b32_e32 v223, 16, v199
	v_and_b32_e32 v199, 0xffff0000, v199
	v_fmac_f32_e32 v44, s20, v223
	v_fmac_f32_e32 v45, s20, v199
	s_waitcnt vmcnt(4)
	v_lshlrev_b32_e32 v222, 16, v200
	v_and_b32_e32 v200, 0xffff0000, v200
	v_fmac_f32_e32 v38, s20, v222
	v_fmac_f32_e32 v39, s20, v200
	v_lshlrev_b32_e32 v223, 16, v201
	v_and_b32_e32 v201, 0xffff0000, v201
	v_fmac_f32_e32 v40, s20, v223
	v_fmac_f32_e32 v41, s20, v201
	v_lshlrev_b32_e32 v222, 16, v202
	v_and_b32_e32 v202, 0xffff0000, v202
	v_fmac_f32_e32 v34, s20, v222
	v_fmac_f32_e32 v35, s20, v202
	v_lshlrev_b32_e32 v223, 16, v203
	v_and_b32_e32 v203, 0xffff0000, v203
	v_fmac_f32_e32 v36, s20, v223
	v_fmac_f32_e32 v37, s20, v203
	s_waitcnt vmcnt(3)
	v_lshlrev_b32_e32 v222, 16, v204
	v_and_b32_e32 v204, 0xffff0000, v204
	v_fmac_f32_e32 v30, s20, v222
	v_fmac_f32_e32 v31, s20, v204
	v_lshlrev_b32_e32 v223, 16, v205
	v_and_b32_e32 v205, 0xffff0000, v205
	v_fmac_f32_e32 v32, s20, v223
	v_fmac_f32_e32 v33, s20, v205
	v_lshlrev_b32_e32 v222, 16, v206
	v_and_b32_e32 v206, 0xffff0000, v206
	v_fmac_f32_e32 v26, s20, v222
	v_fmac_f32_e32 v27, s20, v206
	v_lshlrev_b32_e32 v223, 16, v207
	v_and_b32_e32 v207, 0xffff0000, v207
	v_fmac_f32_e32 v28, s20, v223
	v_fmac_f32_e32 v29, s20, v207
	s_waitcnt vmcnt(2)
	v_lshlrev_b32_e32 v222, 16, v208
	v_and_b32_e32 v208, 0xffff0000, v208
	v_fmac_f32_e32 v22, s20, v222
	v_fmac_f32_e32 v23, s20, v208
	v_lshlrev_b32_e32 v223, 16, v209
	v_and_b32_e32 v209, 0xffff0000, v209
	v_fmac_f32_e32 v24, s20, v223
	v_fmac_f32_e32 v25, s20, v209
	v_lshlrev_b32_e32 v222, 16, v210
	v_and_b32_e32 v210, 0xffff0000, v210
	v_fmac_f32_e32 v18, s20, v222
	v_fmac_f32_e32 v19, s20, v210
	v_lshlrev_b32_e32 v223, 16, v211
	v_and_b32_e32 v211, 0xffff0000, v211
	v_fmac_f32_e32 v20, s20, v223
	v_fmac_f32_e32 v21, s20, v211
	s_waitcnt vmcnt(1)
; #define PG8_BAR __builtin_amdgcn_s_barrier()
; __device__ __forceinline__ float bflo(unsigned w) { return __uint_as_float(w << 16); }
; __device__ __forceinline__ float bfhi(unsigned w) { return __uint_as_float(w & 0xffff0000u); }
; template <class Epi, class Sched, bool ALIGN_EPI = false, bool SP2 = false>
; __device__ __forceinline__ void gemm_phase(PG8_LAS unsigned char* lds, const Gemm g, const Sched& S, const Epi& E) {
;     ...
;         if constexpr (!Epi::AFTER_DRAIN) { E(acc, cur, wr, wc, fr, fq); S.done(cur); }
;         if (!has_next) break;
; #pragma unroll
;         for (int a = 0; a < 2; ++a)
; #pragma unroll
;             for (int b = 0; b < 2; ++b)
; #pragma unroll
;                 for (int m = 0; m < 4; ++m)
; #pragma unroll
;                     for (int n = 0; n < 2; ++n) acc[a][b][m][n] = (f32x4){0.f, 0.f, 0.f, 0.f};
;         cur = nxt; cA = nA; cB = nB; ++ui;
;         if constexpr (ALIGN_EPI) { if (wr == 1) PG8_BAR; }
;     __device__ __forceinline__ void operator()(const pg8::f32x4 (&acc)[2][2][4][2], const pg8::Unit& u, int wr, int wc, int fr, int fq) const {
;     ...
;                     a0[0] += ALPHA * bflo(hw.x); a0[1] += ALPHA * bfhi(hw.x); a0[2] += ALPHA * bflo(hw.y); a0[3] += ALPHA * bfhi(hw.y);
;                     a1[0] += ALPHA * bflo(hw.z); a1[1] += ALPHA * bfhi(hw.z); a1[2] += ALPHA * bflo(hw.w); a1[3] += ALPHA * bfhi(hw.w);
;                     *(pg8::f32x4*)(zr + c) = a0; *(pg8::f32x4*)(zr + c + 4) = a1; } }
	v_lshlrev_b32_e32 v222, 16, v212
	v_and_b32_e32 v212, 0xffff0000, v212
	v_fmac_f32_e32 v14, s20, v222
	v_fmac_f32_e32 v15, s20, v212
	v_lshlrev_b32_e32 v223, 16, v213
	v_and_b32_e32 v213, 0xffff0000, v213
	v_fmac_f32_e32 v16, s20, v223
	v_fmac_f32_e32 v17, s20, v213
	v_lshlrev_b32_e32 v222, 16, v214
	v_and_b32_e32 v214, 0xffff0000, v214
	v_fmac_f32_e32 v10, s20, v222
	v_fmac_f32_e32 v11, s20, v214
	v_lshlrev_b32_e32 v223, 16, v215
	v_and_b32_e32 v215, 0xffff0000, v215
	v_fmac_f32_e32 v12, s20, v223
	v_fmac_f32_e32 v13, s20, v215
	s_waitcnt vmcnt(0)
	v_lshlrev_b32_e32 v222, 16, v216
	v_and_b32_e32 v216, 0xffff0000, v216
	v_fmac_f32_e32 v6, s20, v222
	v_fmac_f32_e32 v7, s20, v216
	v_lshlrev_b32_e32 v223, 16, v217
	v_and_b32_e32 v217, 0xffff0000, v217
	v_fmac_f32_e32 v8, s20, v223
	v_fmac_f32_e32 v9, s20, v217
	v_lshlrev_b32_e32 v222, 16, v218
	v_and_b32_e32 v218, 0xffff0000, v218
	v_fmac_f32_e32 v2, s20, v222
	v_fmac_f32_e32 v3, s20, v218
	v_lshlrev_b32_e32 v223, 16, v219
	v_and_b32_e32 v219, 0xffff0000, v219
	v_fmac_f32_e32 v4, s20, v223
	v_fmac_f32_e32 v5, s20, v219
	global_store_dwordx4 v221, v[126:129], s[100:101]
	global_store_dwordx4 v221, v[122:125], s[100:101] offset:16
	global_store_dwordx4 v221, v[118:121], s[100:101] offset:512
	global_store_dwordx4 v221, v[114:117], s[100:101] offset:528
	s_add_u32 s100, s100, 0x20000
	s_addc_u32 s101, s101, 0
	global_store_dwordx4 v221, v[110:113], s[100:101]
	global_store_dwordx4 v221, v[106:109], s[100:101] offset:16
	global_store_dwordx4 v221, v[102:105], s[100:101] offset:512
	global_store_dwordx4 v221, v[98:101], s[100:101] offset:528
	s_add_u32 s100, s100, 0x20000
	s_addc_u32 s101, s101, 0
	global_store_dwordx4 v221, v[94:97], s[100:101]
	global_store_dwordx4 v221, v[90:93], s[100:101] offset:16
	global_store_dwordx4 v221, v[86:89], s[100:101] offset:512
	global_store_dwordx4 v221, v[82:85], s[100:101] offset:528
	s_add_u32 s100, s100, 0x20000
	s_addc_u32 s101, s101, 0
	global_store_dwordx4 v221, v[78:81], s[100:101]
	global_store_dwordx4 v221, v[74:77], s[100:101] offset:16
	global_store_dwordx4 v221, v[70:73], s[100:101] offset:512
	global_store_dwordx4 v221, v[66:69], s[100:101] offset:528
	s_add_u32 s100, s100, 0xa0000
	s_addc_u32 s101, s101, 0
	global_store_dwordx4 v221, v[62:65], s[100:101]
	global_store_dwordx4 v221, v[58:61], s[100:101] offset:16
	global_store_dwordx4 v221, v[54:57], s[100:101] offset:512
	global_store_dwordx4 v221, v[50:53], s[100:101] offset:528
	s_add_u32 s100, s100, 0x20000
	s_addc_u32 s101, s101, 0
	global_store_dwordx4 v221, v[46:49], s[100:101]
	global_store_dwordx4 v221, v[42:45], s[100:101] offset:16
	global_store_dwordx4 v221, v[38:41], s[100:101] offset:512
	global_store_dwordx4 v221, v[34:37], s[100:101] offset:528
	s_add_u32 s100, s100, 0x20000
	s_addc_u32 s101, s101, 0
	global_store_dwordx4 v221, v[30:33], s[100:101]
	global_store_dwordx4 v221, v[26:29], s[100:101] offset:16
	global_store_dwordx4 v221, v[22:25], s[100:101] offset:512
	global_store_dwordx4 v221, v[18:21], s[100:101] offset:528
	s_add_u32 s100, s100, 0x20000
	s_addc_u32 s101, s101, 0
	global_store_dwordx4 v221, v[14:17], s[100:101]
	global_store_dwordx4 v221, v[10:13], s[100:101] offset:16
	global_store_dwordx4 v221, v[6:9], s[100:101] offset:512
	global_store_dwordx4 v221, v[2:5], s[100:101] offset:528
	s_cbranch_vccnz .LBB0_1375
	s_andn2_b64 vcc, exec, s[10:11]
	s_cbranch_vccnz .LBB0_1374
	s_barrier
	s_branch .LBB0_1374

; __device__ __forceinline__ float bflo(unsigned w) { return __uint_as_float(w << 16); }
; __device__ __forceinline__ float bfhi(unsigned w) { return __uint_as_float(w & 0xffff0000u); }
;     __device__ __forceinline__ void operator()(const pg8::f32x4 (&acc)[2][2][4][2], const pg8::Unit& u, int wr, int wc, int fr, int fq) const {
;         const int row0 = u.pm * 256 + wr * 64 + fr, col0 = u.pn * 256 + wc * 32 + 8 * fq;
; #pragma unroll
;         for (int ai = 0; ai < 2; ++ai)
; #pragma unroll
;             for (int m = 0; m < 4; ++m) { const int row = row0 + ai * 128 + m * 16;
;                 float* zr = Z + (size_t)(row + (MODE == 0 ? NMETA : 0)) * DM;
;                 const bf16_t* hr = H + (size_t)(row + NMETA) * DM;
; #pragma unroll
;                 for (int bj = 0; bj < 2; ++bj) { const int c = col0 + bj * 128; const u32x4 hw = *(const u32x4*)(hr + c);
;                     pg8::f32x4 a0 = acc[ai][bj][m][0], a1 = acc[ai][bj][m][1];
;                     a0[0] += ALPHA * bflo(hw.x); a0[1] += ALPHA * bfhi(hw.x); a0[2] += ALPHA * bflo(hw.y); a0[3] += ALPHA * bfhi(hw.y);
;                     a1[0] += ALPHA * bflo(hw.z); a1[1] += ALPHA * bfhi(hw.z); a1[2] += ALPHA * bflo(hw.w); a1[3] += ALPHA * bfhi(hw.w);
;                     *(pg8::f32x4*)(zr + c) = a0; *(pg8::f32x4*)(zr + c + 4) = a1; } }
.LBB0_2560:
	v_lshl_add_u32 v148, s34, 8, v1
	v_lshl_or_b32 v146, s55, 8, v152
	v_lshlrev_b32_e32 v220, 12, v148
	v_lshl_add_u32 v220, v146, 1, v220
	v_lshlrev_b32_e32 v221, 13, v148
	v_lshl_add_u32 v221, v146, 2, v221
	s_andn2_b64 vcc, exec, s[6:7]
	s_mov_b64 s[6:7], -1
	s_mov_b64 s[98:99], s[12:13]
	global_load_dwordx4 v[146:149], v220, s[98:99]
	global_load_dwordx4 v[158:161], v220, s[98:99] offset:256
	s_add_u32 s98, s98, 0x10000
	s_addc_u32 s99, s99, 0
	global_load_dwordx4 v[162:165], v220, s[98:99]
	global_load_dwordx4 v[166:169], v220, s[98:99] offset:256
	s_add_u32 s98, s98, 0x10000
	s_addc_u32 s99, s99, 0
	global_load_dwordx4 v[170:173], v220, s[98:99]
	global_load_dwordx4 v[174:177], v220, s[98:99] offset:256
	s_add_u32 s98, s98, 0x10000
	s_addc_u32 s99, s99, 0
	global_load_dwordx4 v[178:181], v220, s[98:99]
	global_load_dwordx4 v[182:185], v220, s[98:99] offset:256
	s_add_u32 s98, s98, 0x50000
	s_addc_u32 s99, s99, 0
	global_load_dwordx4 v[186:189], v220, s[98:99]
	global_load_dwordx4 v[190:193], v220, s[98:99] offset:256
	s_add_u32 s98, s98, 0x10000
	s_addc_u32 s99, s99, 0
	global_load_dwordx4 v[196:199], v220, s[98:99]
	global_load_dwordx4 v[200:203], v220, s[98:99] offset:256
	s_add_u32 s98, s98, 0x10000
	s_addc_u32 s99, s99, 0
	global_load_dwordx4 v[204:207], v220, s[98:99]
	global_load_dwordx4 v[208:211], v220, s[98:99] offset:256
	s_add_u32 s98, s98, 0x10000
	s_addc_u32 s99, s99, 0
	global_load_dwordx4 v[212:215], v220, s[98:99]
	global_load_dwordx4 v[216:219], v220, s[98:99] offset:256
	s_mov_b64 s[100:101], s[14:15]
	s_waitcnt vmcnt(15)
	v_lshlrev_b32_e32 v222, 16, v146
	v_and_b32_e32 v146, 0xffff0000, v146
	v_fmac_f32_e32 v126, s22, v222
	v_fmac_f32_e32 v127, s22, v146
	v_lshlrev_b32_e32 v223, 16, v147
	v_and_b32_e32 v147, 0xffff0000, v147
	v_fmac_f32_e32 v128, s22, v223
	v_fmac_f32_e32 v129, s22, v147
	v_lshlrev_b32_e32 v222, 16, v148
	v_and_b32_e32 v148, 0xffff0000, v148
	v_fmac_f32_e32 v122, s22, v222
	v_fmac_f32_e32 v123, s22, v148
	v_lshlrev_b32_e32 v223, 16, v149
	v_and_b32_e32 v149, 0xffff0000, v149
	v_fmac_f32_e32 v124, s22, v223
	v_fmac_f32_e32 v125, s22, v149
	s_waitcnt vmcnt(14)
	v_lshlrev_b32_e32 v222, 16, v158
	v_and_b32_e32 v158, 0xffff0000, v158
	v_fmac_f32_e32 v118, s22, v222
	v_fmac_f32_e32 v119, s22, v158
	v_lshlrev_b32_e32 v223, 16, v159
	v_and_b32_e32 v159, 0xffff0000, v159
	v_fmac_f32_e32 v120, s22, v223
	v_fmac_f32_e32 v121, s22, v159
	v_lshlrev_b32_e32 v222, 16, v160
	v_and_b32_e32 v160, 0xffff0000, v160
	v_fmac_f32_e32 v114, s22, v222
	v_fmac_f32_e32 v115, s22, v160
	v_lshlrev_b32_e32 v223, 16, v161
	v_and_b32_e32 v161, 0xffff0000, v161
	v_fmac_f32_e32 v116, s22, v223
	v_fmac_f32_e32 v117, s22, v161
	s_waitcnt vmcnt(13)
	v_lshlrev_b32_e32 v222, 16, v162
	v_and_b32_e32 v162, 0xffff0000, v162
	v_fmac_f32_e32 v110, s22, v222
	v_fmac_f32_e32 v111, s22, v162
	v_lshlrev_b32_e32 v223, 16, v163
	v_and_b32_e32 v163, 0xffff0000, v163
	v_fmac_f32_e32 v112, s22, v223
	v_fmac_f32_e32 v113, s22, v163
	v_lshlrev_b32_e32 v222, 16, v164
	v_and_b32_e32 v164, 0xffff0000, v164
	v_fmac_f32_e32 v106, s22, v222
	v_fmac_f32_e32 v107, s22, v164
	v_lshlrev_b32_e32 v223, 16, v165
	v_and_b32_e32 v165, 0xffff0000, v165
	v_fmac_f32_e32 v108, s22, v223
	v_fmac_f32_e32 v109, s22, v165
	s_waitcnt vmcnt(12)
	v_lshlrev_b32_e32 v222, 16, v166
	v_and_b32_e32 v166, 0xffff0000, v166
	v_fmac_f32_e32 v102, s22, v222
	v_fmac_f32_e32 v103, s22, v166
	v_lshlrev_b32_e32 v223, 16, v167
	v_and_b32_e32 v167, 0xffff0000, v167
	v_fmac_f32_e32 v104, s22, v223
	v_fmac_f32_e32 v105, s22, v167
	v_lshlrev_b32_e32 v222, 16, v168
	v_and_b32_e32 v168, 0xffff0000, v168
	v_fmac_f32_e32 v98, s22, v222
	v_fmac_f32_e32 v99, s22, v168
	v_lshlrev_b32_e32 v223, 16, v169
	v_and_b32_e32 v169, 0xffff0000, v169
	v_fmac_f32_e32 v100, s22, v223
	v_fmac_f32_e32 v101, s22, v169
	s_waitcnt vmcnt(11)
	v_lshlrev_b32_e32 v222, 16, v170
	v_and_b32_e32 v170, 0xffff0000, v170
	v_fmac_f32_e32 v94, s22, v222
	v_fmac_f32_e32 v95, s22, v170
	v_lshlrev_b32_e32 v223, 16, v171
	v_and_b32_e32 v171, 0xffff0000, v171
	v_fmac_f32_e32 v96, s22, v223
	v_fmac_f32_e32 v97, s22, v171
	v_lshlrev_b32_e32 v222, 16, v172
	v_and_b32_e32 v172, 0xffff0000, v172
	v_fmac_f32_e32 v90, s22, v222
	v_fmac_f32_e32 v91, s22, v172
	v_lshlrev_b32_e32 v223, 16, v173
	v_and_b32_e32 v173, 0xffff0000, v173
	v_fmac_f32_e32 v92, s22, v223
	v_fmac_f32_e32 v93, s22, v173
	s_waitcnt vmcnt(10)
	v_lshlrev_b32_e32 v222, 16, v174
	v_and_b32_e32 v174, 0xffff0000, v174
	v_fmac_f32_e32 v86, s22, v222
	v_fmac_f32_e32 v87, s22, v174
	v_lshlrev_b32_e32 v223, 16, v175
	v_and_b32_e32 v175, 0xffff0000, v175
	v_fmac_f32_e32 v88, s22, v223
	v_fmac_f32_e32 v89, s22, v175
	v_lshlrev_b32_e32 v222, 16, v176
	v_and_b32_e32 v176, 0xffff0000, v176
	v_fmac_f32_e32 v82, s22, v222
	v_fmac_f32_e32 v83, s22, v176
	v_lshlrev_b32_e32 v223, 16, v177
	v_and_b32_e32 v177, 0xffff0000, v177
	v_fmac_f32_e32 v84, s22, v223
	v_fmac_f32_e32 v85, s22, v177
	s_waitcnt vmcnt(9)
	v_lshlrev_b32_e32 v222, 16, v178
	v_and_b32_e32 v178, 0xffff0000, v178
	v_fmac_f32_e32 v78, s22, v222
	v_fmac_f32_e32 v79, s22, v178
	v_lshlrev_b32_e32 v223, 16, v179
	v_and_b32_e32 v179, 0xffff0000, v179
	v_fmac_f32_e32 v80, s22, v223
	v_fmac_f32_e32 v81, s22, v179
	v_lshlrev_b32_e32 v222, 16, v180
	v_and_b32_e32 v180, 0xffff0000, v180
	v_fmac_f32_e32 v74, s22, v222
	v_fmac_f32_e32 v75, s22, v180
	v_lshlrev_b32_e32 v223, 16, v181
	v_and_b32_e32 v181, 0xffff0000, v181
	v_fmac_f32_e32 v76, s22, v223
	v_fmac_f32_e32 v77, s22, v181
	s_waitcnt vmcnt(8)
; __device__ __forceinline__ float bflo(unsigned w) { return __uint_as_float(w << 16); }
; __device__ __forceinline__ float bfhi(unsigned w) { return __uint_as_float(w & 0xffff0000u); }
;     __device__ __forceinline__ void operator()(const pg8::f32x4 (&acc)[2][2][4][2], const pg8::Unit& u, int wr, int wc, int fr, int fq) const {
;     ...
;                     a0[0] += ALPHA * bflo(hw.x); a0[1] += ALPHA * bfhi(hw.x); a0[2] += ALPHA * bflo(hw.y); a0[3] += ALPHA * bfhi(hw.y);
;                     a1[0] += ALPHA * bflo(hw.z); a1[1] += ALPHA * bfhi(hw.z); a1[2] += ALPHA * bflo(hw.w); a1[3] += ALPHA * bfhi(hw.w);
;                     *(pg8::f32x4*)(zr + c) = a0; *(pg8::f32x4*)(zr + c + 4) = a1; } }
	v_lshlrev_b32_e32 v222, 16, v182
	v_and_b32_e32 v182, 0xffff0000, v182
	v_fmac_f32_e32 v70, s22, v222
	v_fmac_f32_e32 v71, s22, v182
	v_lshlrev_b32_e32 v223, 16, v183
	v_and_b32_e32 v183, 0xffff0000, v183
	v_fmac_f32_e32 v72, s22, v223
	v_fmac_f32_e32 v73, s22, v183
	v_lshlrev_b32_e32 v222, 16, v184
	v_and_b32_e32 v184, 0xffff0000, v184
	v_fmac_f32_e32 v66, s22, v222
	v_fmac_f32_e32 v67, s22, v184
	v_lshlrev_b32_e32 v223, 16, v185
	v_and_b32_e32 v185, 0xffff0000, v185
	v_fmac_f32_e32 v68, s22, v223
	v_fmac_f32_e32 v69, s22, v185
	s_waitcnt vmcnt(7)
	v_lshlrev_b32_e32 v222, 16, v186
	v_and_b32_e32 v186, 0xffff0000, v186
	v_fmac_f32_e32 v62, s22, v222
	v_fmac_f32_e32 v63, s22, v186
	v_lshlrev_b32_e32 v223, 16, v187
	v_and_b32_e32 v187, 0xffff0000, v187
	v_fmac_f32_e32 v64, s22, v223
	v_fmac_f32_e32 v65, s22, v187
	v_lshlrev_b32_e32 v222, 16, v188
	v_and_b32_e32 v188, 0xffff0000, v188
	v_fmac_f32_e32 v58, s22, v222
	v_fmac_f32_e32 v59, s22, v188
	v_lshlrev_b32_e32 v223, 16, v189
	v_and_b32_e32 v189, 0xffff0000, v189
	v_fmac_f32_e32 v60, s22, v223
	v_fmac_f32_e32 v61, s22, v189
	s_waitcnt vmcnt(6)
	v_lshlrev_b32_e32 v222, 16, v190
	v_and_b32_e32 v190, 0xffff0000, v190
	v_fmac_f32_e32 v54, s22, v222
	v_fmac_f32_e32 v55, s22, v190
	v_lshlrev_b32_e32 v223, 16, v191
	v_and_b32_e32 v191, 0xffff0000, v191
	v_fmac_f32_e32 v56, s22, v223
	v_fmac_f32_e32 v57, s22, v191
	v_lshlrev_b32_e32 v222, 16, v192
	v_and_b32_e32 v192, 0xffff0000, v192
	v_fmac_f32_e32 v50, s22, v222
	v_fmac_f32_e32 v51, s22, v192
	v_lshlrev_b32_e32 v223, 16, v193
	v_and_b32_e32 v193, 0xffff0000, v193
	v_fmac_f32_e32 v52, s22, v223
	v_fmac_f32_e32 v53, s22, v193
	s_waitcnt vmcnt(5)
	v_lshlrev_b32_e32 v222, 16, v196
	v_and_b32_e32 v196, 0xffff0000, v196
	v_fmac_f32_e32 v46, s22, v222
	v_fmac_f32_e32 v47, s22, v196
	v_lshlrev_b32_e32 v223, 16, v197
	v_and_b32_e32 v197, 0xffff0000, v197
	v_fmac_f32_e32 v48, s22, v223
	v_fmac_f32_e32 v49, s22, v197
	v_lshlrev_b32_e32 v222, 16, v198
	v_and_b32_e32 v198, 0xffff0000, v198
	v_fmac_f32_e32 v42, s22, v222
	v_fmac_f32_e32 v43, s22, v198
	v_lshlrev_b32_e32 v223, 16, v199
	v_and_b32_e32 v199, 0xffff0000, v199
	v_fmac_f32_e32 v44, s22, v223
	v_fmac_f32_e32 v45, s22, v199
	s_waitcnt vmcnt(4)
	v_lshlrev_b32_e32 v222, 16, v200
	v_and_b32_e32 v200, 0xffff0000, v200
	v_fmac_f32_e32 v38, s22, v222
	v_fmac_f32_e32 v39, s22, v200
	v_lshlrev_b32_e32 v223, 16, v201
	v_and_b32_e32 v201, 0xffff0000, v201
	v_fmac_f32_e32 v40, s22, v223
	v_fmac_f32_e32 v41, s22, v201
	v_lshlrev_b32_e32 v222, 16, v202
	v_and_b32_e32 v202, 0xffff0000, v202
	v_fmac_f32_e32 v34, s22, v222
	v_fmac_f32_e32 v35, s22, v202
	v_lshlrev_b32_e32 v223, 16, v203
	v_and_b32_e32 v203, 0xffff0000, v203
	v_fmac_f32_e32 v36, s22, v223
	v_fmac_f32_e32 v37, s22, v203
	s_waitcnt vmcnt(3)
	v_lshlrev_b32_e32 v222, 16, v204
	v_and_b32_e32 v204, 0xffff0000, v204
	v_fmac_f32_e32 v30, s22, v222
	v_fmac_f32_e32 v31, s22, v204
	v_lshlrev_b32_e32 v223, 16, v205
	v_and_b32_e32 v205, 0xffff0000, v205
	v_fmac_f32_e32 v32, s22, v223
	v_fmac_f32_e32 v33, s22, v205
	v_lshlrev_b32_e32 v222, 16, v206
	v_and_b32_e32 v206, 0xffff0000, v206
	v_fmac_f32_e32 v26, s22, v222
	v_fmac_f32_e32 v27, s22, v206
	v_lshlrev_b32_e32 v223, 16, v207
	v_and_b32_e32 v207, 0xffff0000, v207
	v_fmac_f32_e32 v28, s22, v223
	v_fmac_f32_e32 v29, s22, v207
	s_waitcnt vmcnt(2)
	v_lshlrev_b32_e32 v222, 16, v208
	v_and_b32_e32 v208, 0xffff0000, v208
	v_fmac_f32_e32 v22, s22, v222
	v_fmac_f32_e32 v23, s22, v208
	v_lshlrev_b32_e32 v223, 16, v209
	v_and_b32_e32 v209, 0xffff0000, v209
	v_fmac_f32_e32 v24, s22, v223
	v_fmac_f32_e32 v25, s22, v209
	v_lshlrev_b32_e32 v222, 16, v210
	v_and_b32_e32 v210, 0xffff0000, v210
	v_fmac_f32_e32 v18, s22, v222
	v_fmac_f32_e32 v19, s22, v210
	v_lshlrev_b32_e32 v223, 16, v211
	v_and_b32_e32 v211, 0xffff0000, v211
	v_fmac_f32_e32 v20, s22, v223
	v_fmac_f32_e32 v21, s22, v211
	s_waitcnt vmcnt(1)
; #define PG8_BAR __builtin_amdgcn_s_barrier()
; __device__ __forceinline__ float bflo(unsigned w) { return __uint_as_float(w << 16); }
; __device__ __forceinline__ float bfhi(unsigned w) { return __uint_as_float(w & 0xffff0000u); }
; template <class Epi, class Sched, bool ALIGN_EPI = false, bool SP2 = false>
; __device__ __forceinline__ void gemm_phase(PG8_LAS unsigned char* lds, const Gemm g, const Sched& S, const Epi& E) {
;     ...
;         if (!has_next) break;
; #pragma unroll
;         for (int a = 0; a < 2; ++a)
; #pragma unroll
;             for (int b = 0; b < 2; ++b)
; #pragma unroll
;                 for (int m = 0; m < 4; ++m)
; #pragma unroll
;                     for (int n = 0; n < 2; ++n) acc[a][b][m][n] = (f32x4){0.f, 0.f, 0.f, 0.f};
;         cur = nxt; cA = nA; cB = nB; ++ui;
;         if constexpr (ALIGN_EPI) { if (wr == 1) PG8_BAR; }
;     __device__ __forceinline__ void operator()(const pg8::f32x4 (&acc)[2][2][4][2], const pg8::Unit& u, int wr, int wc, int fr, int fq) const {
;     ...
;                     a0[0] += ALPHA * bflo(hw.x); a0[1] += ALPHA * bfhi(hw.x); a0[2] += ALPHA * bflo(hw.y); a0[3] += ALPHA * bfhi(hw.y);
;                     a1[0] += ALPHA * bflo(hw.z); a1[1] += ALPHA * bfhi(hw.z); a1[2] += ALPHA * bflo(hw.w); a1[3] += ALPHA * bfhi(hw.w);
;                     *(pg8::f32x4*)(zr + c) = a0; *(pg8::f32x4*)(zr + c + 4) = a1; } }
	v_lshlrev_b32_e32 v222, 16, v212
	v_and_b32_e32 v212, 0xffff0000, v212
	v_fmac_f32_e32 v14, s22, v222
	v_fmac_f32_e32 v15, s22, v212
	v_lshlrev_b32_e32 v223, 16, v213
	v_and_b32_e32 v213, 0xffff0000, v213
	v_fmac_f32_e32 v16, s22, v223
	v_fmac_f32_e32 v17, s22, v213
	v_lshlrev_b32_e32 v222, 16, v214
	v_and_b32_e32 v214, 0xffff0000, v214
	v_fmac_f32_e32 v10, s22, v222
	v_fmac_f32_e32 v11, s22, v214
	v_lshlrev_b32_e32 v223, 16, v215
	v_and_b32_e32 v215, 0xffff0000, v215
	v_fmac_f32_e32 v12, s22, v223
	v_fmac_f32_e32 v13, s22, v215
	s_waitcnt vmcnt(0)
	v_lshlrev_b32_e32 v222, 16, v216
	v_and_b32_e32 v216, 0xffff0000, v216
	v_fmac_f32_e32 v6, s22, v222
	v_fmac_f32_e32 v7, s22, v216
	v_lshlrev_b32_e32 v223, 16, v217
	v_and_b32_e32 v217, 0xffff0000, v217
	v_fmac_f32_e32 v8, s22, v223
	v_fmac_f32_e32 v9, s22, v217
	v_lshlrev_b32_e32 v222, 16, v218
	v_and_b32_e32 v218, 0xffff0000, v218
	v_fmac_f32_e32 v2, s22, v222
	v_fmac_f32_e32 v3, s22, v218
	v_lshlrev_b32_e32 v223, 16, v219
	v_and_b32_e32 v219, 0xffff0000, v219
	v_fmac_f32_e32 v4, s22, v223
	v_fmac_f32_e32 v5, s22, v219
	global_store_dwordx4 v221, v[126:129], s[100:101]
	global_store_dwordx4 v221, v[122:125], s[100:101] offset:16
	global_store_dwordx4 v221, v[118:121], s[100:101] offset:512
	global_store_dwordx4 v221, v[114:117], s[100:101] offset:528
	s_add_u32 s100, s100, 0x20000
	s_addc_u32 s101, s101, 0
	global_store_dwordx4 v221, v[110:113], s[100:101]
	global_store_dwordx4 v221, v[106:109], s[100:101] offset:16
	global_store_dwordx4 v221, v[102:105], s[100:101] offset:512
	global_store_dwordx4 v221, v[98:101], s[100:101] offset:528
	s_add_u32 s100, s100, 0x20000
	s_addc_u32 s101, s101, 0
	global_store_dwordx4 v221, v[94:97], s[100:101]
	global_store_dwordx4 v221, v[90:93], s[100:101] offset:16
	global_store_dwordx4 v221, v[86:89], s[100:101] offset:512
	global_store_dwordx4 v221, v[82:85], s[100:101] offset:528
	s_add_u32 s100, s100, 0x20000
	s_addc_u32 s101, s101, 0
	global_store_dwordx4 v221, v[78:81], s[100:101]
	global_store_dwordx4 v221, v[74:77], s[100:101] offset:16
	global_store_dwordx4 v221, v[70:73], s[100:101] offset:512
	global_store_dwordx4 v221, v[66:69], s[100:101] offset:528
	s_add_u32 s100, s100, 0xa0000
	s_addc_u32 s101, s101, 0
	global_store_dwordx4 v221, v[62:65], s[100:101]
	global_store_dwordx4 v221, v[58:61], s[100:101] offset:16
	global_store_dwordx4 v221, v[54:57], s[100:101] offset:512
	global_store_dwordx4 v221, v[50:53], s[100:101] offset:528
	s_add_u32 s100, s100, 0x20000
	s_addc_u32 s101, s101, 0
	global_store_dwordx4 v221, v[46:49], s[100:101]
	global_store_dwordx4 v221, v[42:45], s[100:101] offset:16
	global_store_dwordx4 v221, v[38:41], s[100:101] offset:512
	global_store_dwordx4 v221, v[34:37], s[100:101] offset:528
	s_add_u32 s100, s100, 0x20000
	s_addc_u32 s101, s101, 0
	global_store_dwordx4 v221, v[30:33], s[100:101]
	global_store_dwordx4 v221, v[26:29], s[100:101] offset:16
	global_store_dwordx4 v221, v[22:25], s[100:101] offset:512
	global_store_dwordx4 v221, v[18:21], s[100:101] offset:528
	s_add_u32 s100, s100, 0x20000
	s_addc_u32 s101, s101, 0
	global_store_dwordx4 v221, v[14:17], s[100:101]
	global_store_dwordx4 v221, v[10:13], s[100:101] offset:16
	global_store_dwordx4 v221, v[6:9], s[100:101] offset:512
	global_store_dwordx4 v221, v[2:5], s[100:101] offset:528
	s_cbranch_vccnz .LBB0_2549
	s_andn2_b64 vcc, exec, s[16:17]
	s_cbranch_vccnz .LBB0_2548
	s_barrier
	s_branch .LBB0_2548

; __device__ __forceinline__ float bflo(unsigned w) { return __uint_as_float(w << 16); }
; __device__ __forceinline__ float bfhi(unsigned w) { return __uint_as_float(w & 0xffff0000u); }
;     __device__ __forceinline__ void operator()(const pg8::f32x4 (&acc)[2][2][4][2], const pg8::Unit& u, int wr, int wc, int fr, int fq) const {
;         const int row0 = u.pm * 256 + wr * 64 + fr, col0 = u.pn * 256 + wc * 32 + 8 * fq;
; #pragma unroll
;         for (int ai = 0; ai < 2; ++ai)
; #pragma unroll
;             for (int m = 0; m < 4; ++m) { const int row = row0 + ai * 128 + m * 16;
;                 float* zr = Z + (size_t)(row + (MODE == 0 ? NMETA : 0)) * DM;
;                 const bf16_t* hr = H + (size_t)(row + NMETA) * DM;
; #pragma unroll
;                 for (int bj = 0; bj < 2; ++bj) { const int c = col0 + bj * 128; const u32x4 hw = *(const u32x4*)(hr + c);
;                     pg8::f32x4 a0 = acc[ai][bj][m][0], a1 = acc[ai][bj][m][1];
;                     a0[0] += ALPHA * bflo(hw.x); a0[1] += ALPHA * bfhi(hw.x); a0[2] += ALPHA * bflo(hw.y); a0[3] += ALPHA * bfhi(hw.y);
;                     a1[0] += ALPHA * bflo(hw.z); a1[1] += ALPHA * bfhi(hw.z); a1[2] += ALPHA * bflo(hw.w); a1[3] += ALPHA * bfhi(hw.w);
;                     *(pg8::f32x4*)(zr + c) = a0; *(pg8::f32x4*)(zr + c + 4) = a1; } }
.LBB0_2814:
	v_lshl_add_u32 v148, s42, 8, v1
	v_or_b32_e32 v164, 16, v148
	v_lshl_or_b32 v146, s64, 8, v154
	v_lshlrev_b32_e32 v220, 12, v164
	v_lshl_add_u32 v220, v146, 1, v220
	v_lshlrev_b32_e32 v221, 13, v148
	v_lshl_add_u32 v221, v146, 2, v221
	s_nop 0
	s_andn2_b64 vcc, exec, s[6:7]
	s_mov_b64 s[6:7], -1
	s_mov_b64 s[98:99], s[16:17]
	global_load_dwordx4 v[146:149], v220, s[98:99]
	global_load_dwordx4 v[150:153], v220, s[98:99] offset:256
	s_add_u32 s98, s98, 0x10000
	s_addc_u32 s99, s99, 0
	global_load_dwordx4 v[160:163], v220, s[98:99]
	global_load_dwordx4 v[164:167], v220, s[98:99] offset:256
	s_add_u32 s98, s98, 0x10000
	s_addc_u32 s99, s99, 0
	global_load_dwordx4 v[168:171], v220, s[98:99]
	global_load_dwordx4 v[172:175], v220, s[98:99] offset:256
	s_add_u32 s98, s98, 0x10000
	s_addc_u32 s99, s99, 0
	global_load_dwordx4 v[176:179], v220, s[98:99]
	global_load_dwordx4 v[180:183], v220, s[98:99] offset:256
	s_add_u32 s98, s98, 0x50000
	s_addc_u32 s99, s99, 0
	global_load_dwordx4 v[184:187], v220, s[98:99]
	global_load_dwordx4 v[188:191], v220, s[98:99] offset:256
	s_add_u32 s98, s98, 0x10000
	s_addc_u32 s99, s99, 0
	global_load_dwordx4 v[196:199], v220, s[98:99]
	global_load_dwordx4 v[200:203], v220, s[98:99] offset:256
	s_add_u32 s98, s98, 0x10000
	s_addc_u32 s99, s99, 0
	global_load_dwordx4 v[204:207], v220, s[98:99]
	global_load_dwordx4 v[208:211], v220, s[98:99] offset:256
	s_add_u32 s98, s98, 0x10000
	s_addc_u32 s99, s99, 0
	global_load_dwordx4 v[212:215], v220, s[98:99]
	global_load_dwordx4 v[216:219], v220, s[98:99] offset:256
	s_mov_b64 s[100:101], s[8:9]
	s_waitcnt vmcnt(15)
	v_lshlrev_b32_e32 v222, 16, v146
	v_and_b32_e32 v146, 0xffff0000, v146
	v_fmac_f32_e32 v126, s22, v222
	v_fmac_f32_e32 v127, s22, v146
	v_lshlrev_b32_e32 v223, 16, v147
	v_and_b32_e32 v147, 0xffff0000, v147
	v_fmac_f32_e32 v128, s22, v223
	v_fmac_f32_e32 v129, s22, v147
	v_lshlrev_b32_e32 v222, 16, v148
	v_and_b32_e32 v148, 0xffff0000, v148
	v_fmac_f32_e32 v122, s22, v222
	v_fmac_f32_e32 v123, s22, v148
	v_lshlrev_b32_e32 v223, 16, v149
	v_and_b32_e32 v149, 0xffff0000, v149
	v_fmac_f32_e32 v124, s22, v223
	v_fmac_f32_e32 v125, s22, v149
	s_waitcnt vmcnt(14)
	v_lshlrev_b32_e32 v222, 16, v150
	v_and_b32_e32 v150, 0xffff0000, v150
	v_fmac_f32_e32 v118, s22, v222
	v_fmac_f32_e32 v119, s22, v150
	v_lshlrev_b32_e32 v223, 16, v151
	v_and_b32_e32 v151, 0xffff0000, v151
	v_fmac_f32_e32 v120, s22, v223
	v_fmac_f32_e32 v121, s22, v151
	v_lshlrev_b32_e32 v222, 16, v152
	v_and_b32_e32 v152, 0xffff0000, v152
	v_fmac_f32_e32 v114, s22, v222
	v_fmac_f32_e32 v115, s22, v152
	v_lshlrev_b32_e32 v223, 16, v153
	v_and_b32_e32 v153, 0xffff0000, v153
	v_fmac_f32_e32 v116, s22, v223
	v_fmac_f32_e32 v117, s22, v153
	s_waitcnt vmcnt(13)
	v_lshlrev_b32_e32 v222, 16, v160
	v_and_b32_e32 v160, 0xffff0000, v160
	v_fmac_f32_e32 v110, s22, v222
	v_fmac_f32_e32 v111, s22, v160
	v_lshlrev_b32_e32 v223, 16, v161
	v_and_b32_e32 v161, 0xffff0000, v161
	v_fmac_f32_e32 v112, s22, v223
	v_fmac_f32_e32 v113, s22, v161
	v_lshlrev_b32_e32 v222, 16, v162
	v_and_b32_e32 v162, 0xffff0000, v162
	v_fmac_f32_e32 v106, s22, v222
	v_fmac_f32_e32 v107, s22, v162
	v_lshlrev_b32_e32 v223, 16, v163
	v_and_b32_e32 v163, 0xffff0000, v163
	v_fmac_f32_e32 v108, s22, v223
	v_fmac_f32_e32 v109, s22, v163
	s_waitcnt vmcnt(12)
	v_lshlrev_b32_e32 v222, 16, v164
	v_and_b32_e32 v164, 0xffff0000, v164
	v_fmac_f32_e32 v102, s22, v222
	v_fmac_f32_e32 v103, s22, v164
	v_lshlrev_b32_e32 v223, 16, v165
	v_and_b32_e32 v165, 0xffff0000, v165
	v_fmac_f32_e32 v104, s22, v223
	v_fmac_f32_e32 v105, s22, v165
	v_lshlrev_b32_e32 v222, 16, v166
	v_and_b32_e32 v166, 0xffff0000, v166
	v_fmac_f32_e32 v98, s22, v222
	v_fmac_f32_e32 v99, s22, v166
	v_lshlrev_b32_e32 v223, 16, v167
	v_and_b32_e32 v167, 0xffff0000, v167
	v_fmac_f32_e32 v100, s22, v223
	v_fmac_f32_e32 v101, s22, v167
	s_waitcnt vmcnt(11)
	v_lshlrev_b32_e32 v222, 16, v168
	v_and_b32_e32 v168, 0xffff0000, v168
	v_fmac_f32_e32 v94, s22, v222
	v_fmac_f32_e32 v95, s22, v168
	v_lshlrev_b32_e32 v223, 16, v169
	v_and_b32_e32 v169, 0xffff0000, v169
	v_fmac_f32_e32 v96, s22, v223
	v_fmac_f32_e32 v97, s22, v169
	v_lshlrev_b32_e32 v222, 16, v170
	v_and_b32_e32 v170, 0xffff0000, v170
	v_fmac_f32_e32 v90, s22, v222
	v_fmac_f32_e32 v91, s22, v170
	v_lshlrev_b32_e32 v223, 16, v171
	v_and_b32_e32 v171, 0xffff0000, v171
	v_fmac_f32_e32 v92, s22, v223
	v_fmac_f32_e32 v93, s22, v171
	s_waitcnt vmcnt(10)
	v_lshlrev_b32_e32 v222, 16, v172
	v_and_b32_e32 v172, 0xffff0000, v172
	v_fmac_f32_e32 v86, s22, v222
	v_fmac_f32_e32 v87, s22, v172
	v_lshlrev_b32_e32 v223, 16, v173
	v_and_b32_e32 v173, 0xffff0000, v173
	v_fmac_f32_e32 v88, s22, v223
	v_fmac_f32_e32 v89, s22, v173
	v_lshlrev_b32_e32 v222, 16, v174
	v_and_b32_e32 v174, 0xffff0000, v174
	v_fmac_f32_e32 v82, s22, v222
	v_fmac_f32_e32 v83, s22, v174
	v_lshlrev_b32_e32 v223, 16, v175
	v_and_b32_e32 v175, 0xffff0000, v175
	v_fmac_f32_e32 v84, s22, v223
	v_fmac_f32_e32 v85, s22, v175
	s_waitcnt vmcnt(9)
	v_lshlrev_b32_e32 v222, 16, v176
	v_and_b32_e32 v176, 0xffff0000, v176
	v_fmac_f32_e32 v78, s22, v222
	v_fmac_f32_e32 v79, s22, v176
	v_lshlrev_b32_e32 v223, 16, v177
	v_and_b32_e32 v177, 0xffff0000, v177
	v_fmac_f32_e32 v80, s22, v223
	v_fmac_f32_e32 v81, s22, v177
	v_lshlrev_b32_e32 v222, 16, v178
	v_and_b32_e32 v178, 0xffff0000, v178
	v_fmac_f32_e32 v74, s22, v222
	v_fmac_f32_e32 v75, s22, v178
	v_lshlrev_b32_e32 v223, 16, v179
	v_and_b32_e32 v179, 0xffff0000, v179
	v_fmac_f32_e32 v76, s22, v223
	v_fmac_f32_e32 v77, s22, v179
	s_waitcnt vmcnt(8)
; __device__ __forceinline__ float bflo(unsigned w) { return __uint_as_float(w << 16); }
; __device__ __forceinline__ float bfhi(unsigned w) { return __uint_as_float(w & 0xffff0000u); }
;     __device__ __forceinline__ void operator()(const pg8::f32x4 (&acc)[2][2][4][2], const pg8::Unit& u, int wr, int wc, int fr, int fq) const {
;     ...
;                     a0[0] += ALPHA * bflo(hw.x); a0[1] += ALPHA * bfhi(hw.x); a0[2] += ALPHA * bflo(hw.y); a0[3] += ALPHA * bfhi(hw.y);
;                     a1[0] += ALPHA * bflo(hw.z); a1[1] += ALPHA * bfhi(hw.z); a1[2] += ALPHA * bflo(hw.w); a1[3] += ALPHA * bfhi(hw.w);
;                     *(pg8::f32x4*)(zr + c) = a0; *(pg8::f32x4*)(zr + c + 4) = a1; } }
	v_lshlrev_b32_e32 v222, 16, v180
	v_and_b32_e32 v180, 0xffff0000, v180
	v_fmac_f32_e32 v70, s22, v222
	v_fmac_f32_e32 v71, s22, v180
	v_lshlrev_b32_e32 v223, 16, v181
	v_and_b32_e32 v181, 0xffff0000, v181
	v_fmac_f32_e32 v72, s22, v223
	v_fmac_f32_e32 v73, s22, v181
	v_lshlrev_b32_e32 v222, 16, v182
	v_and_b32_e32 v182, 0xffff0000, v182
	v_fmac_f32_e32 v66, s22, v222
	v_fmac_f32_e32 v67, s22, v182
	v_lshlrev_b32_e32 v223, 16, v183
	v_and_b32_e32 v183, 0xffff0000, v183
	v_fmac_f32_e32 v68, s22, v223
	v_fmac_f32_e32 v69, s22, v183
	s_waitcnt vmcnt(7)
	v_lshlrev_b32_e32 v222, 16, v184
	v_and_b32_e32 v184, 0xffff0000, v184
	v_fmac_f32_e32 v62, s22, v222
	v_fmac_f32_e32 v63, s22, v184
	v_lshlrev_b32_e32 v223, 16, v185
	v_and_b32_e32 v185, 0xffff0000, v185
	v_fmac_f32_e32 v64, s22, v223
	v_fmac_f32_e32 v65, s22, v185
	v_lshlrev_b32_e32 v222, 16, v186
	v_and_b32_e32 v186, 0xffff0000, v186
	v_fmac_f32_e32 v58, s22, v222
	v_fmac_f32_e32 v59, s22, v186
	v_lshlrev_b32_e32 v223, 16, v187
	v_and_b32_e32 v187, 0xffff0000, v187
	v_fmac_f32_e32 v60, s22, v223
	v_fmac_f32_e32 v61, s22, v187
	s_waitcnt vmcnt(6)
	v_lshlrev_b32_e32 v222, 16, v188
	v_and_b32_e32 v188, 0xffff0000, v188
	v_fmac_f32_e32 v54, s22, v222
	v_fmac_f32_e32 v55, s22, v188
	v_lshlrev_b32_e32 v223, 16, v189
	v_and_b32_e32 v189, 0xffff0000, v189
	v_fmac_f32_e32 v56, s22, v223
	v_fmac_f32_e32 v57, s22, v189
	v_lshlrev_b32_e32 v222, 16, v190
	v_and_b32_e32 v190, 0xffff0000, v190
	v_fmac_f32_e32 v50, s22, v222
	v_fmac_f32_e32 v51, s22, v190
	v_lshlrev_b32_e32 v223, 16, v191
	v_and_b32_e32 v191, 0xffff0000, v191
	v_fmac_f32_e32 v52, s22, v223
	v_fmac_f32_e32 v53, s22, v191
	s_waitcnt vmcnt(5)
	v_lshlrev_b32_e32 v222, 16, v196
	v_and_b32_e32 v196, 0xffff0000, v196
	v_fmac_f32_e32 v46, s22, v222
	v_fmac_f32_e32 v47, s22, v196
	v_lshlrev_b32_e32 v223, 16, v197
	v_and_b32_e32 v197, 0xffff0000, v197
	v_fmac_f32_e32 v48, s22, v223
	v_fmac_f32_e32 v49, s22, v197
	v_lshlrev_b32_e32 v222, 16, v198
	v_and_b32_e32 v198, 0xffff0000, v198
	v_fmac_f32_e32 v42, s22, v222
	v_fmac_f32_e32 v43, s22, v198
	v_lshlrev_b32_e32 v223, 16, v199
	v_and_b32_e32 v199, 0xffff0000, v199
	v_fmac_f32_e32 v44, s22, v223
	v_fmac_f32_e32 v45, s22, v199
	s_waitcnt vmcnt(4)
	v_lshlrev_b32_e32 v222, 16, v200
	v_and_b32_e32 v200, 0xffff0000, v200
	v_fmac_f32_e32 v38, s22, v222
	v_fmac_f32_e32 v39, s22, v200
	v_lshlrev_b32_e32 v223, 16, v201
	v_and_b32_e32 v201, 0xffff0000, v201
	v_fmac_f32_e32 v40, s22, v223
	v_fmac_f32_e32 v41, s22, v201
	v_lshlrev_b32_e32 v222, 16, v202
	v_and_b32_e32 v202, 0xffff0000, v202
	v_fmac_f32_e32 v34, s22, v222
	v_fmac_f32_e32 v35, s22, v202
	v_lshlrev_b32_e32 v223, 16, v203
	v_and_b32_e32 v203, 0xffff0000, v203
	v_fmac_f32_e32 v36, s22, v223
	v_fmac_f32_e32 v37, s22, v203
	s_waitcnt vmcnt(3)
	v_lshlrev_b32_e32 v222, 16, v204
	v_and_b32_e32 v204, 0xffff0000, v204
	v_fmac_f32_e32 v30, s22, v222
	v_fmac_f32_e32 v31, s22, v204
	v_lshlrev_b32_e32 v223, 16, v205
	v_and_b32_e32 v205, 0xffff0000, v205
	v_fmac_f32_e32 v32, s22, v223
	v_fmac_f32_e32 v33, s22, v205
	v_lshlrev_b32_e32 v222, 16, v206
	v_and_b32_e32 v206, 0xffff0000, v206
	v_fmac_f32_e32 v26, s22, v222
	v_fmac_f32_e32 v27, s22, v206
	v_lshlrev_b32_e32 v223, 16, v207
	v_and_b32_e32 v207, 0xffff0000, v207
	v_fmac_f32_e32 v28, s22, v223
	v_fmac_f32_e32 v29, s22, v207
	s_waitcnt vmcnt(2)
	v_lshlrev_b32_e32 v222, 16, v208
	v_and_b32_e32 v208, 0xffff0000, v208
	v_fmac_f32_e32 v22, s22, v222
	v_fmac_f32_e32 v23, s22, v208
	v_lshlrev_b32_e32 v223, 16, v209
	v_and_b32_e32 v209, 0xffff0000, v209
	v_fmac_f32_e32 v24, s22, v223
	v_fmac_f32_e32 v25, s22, v209
	v_lshlrev_b32_e32 v222, 16, v210
	v_and_b32_e32 v210, 0xffff0000, v210
	v_fmac_f32_e32 v18, s22, v222
	v_fmac_f32_e32 v19, s22, v210
	v_lshlrev_b32_e32 v223, 16, v211
	v_and_b32_e32 v211, 0xffff0000, v211
	v_fmac_f32_e32 v20, s22, v223
	v_fmac_f32_e32 v21, s22, v211
	s_waitcnt vmcnt(1)
; #define PG8_BAR __builtin_amdgcn_s_barrier()
; __device__ __forceinline__ float bflo(unsigned w) { return __uint_as_float(w << 16); }
; __device__ __forceinline__ float bfhi(unsigned w) { return __uint_as_float(w & 0xffff0000u); }
; template <class Epi, class Sched, bool ALIGN_EPI = false, bool SP2 = false>
; __device__ __forceinline__ void gemm_phase(PG8_LAS unsigned char* lds, const Gemm g, const Sched& S, const Epi& E) {
;     ...
;         if (!has_next) break;
; #pragma unroll
;         for (int a = 0; a < 2; ++a)
; #pragma unroll
;             for (int b = 0; b < 2; ++b)
; #pragma unroll
;                 for (int m = 0; m < 4; ++m)
; #pragma unroll
;                     for (int n = 0; n < 2; ++n) acc[a][b][m][n] = (f32x4){0.f, 0.f, 0.f, 0.f};
;         cur = nxt; cA = nA; cB = nB; ++ui;
;         if constexpr (ALIGN_EPI) { if (wr == 1) PG8_BAR; }
;     __device__ __forceinline__ void operator()(const pg8::f32x4 (&acc)[2][2][4][2], const pg8::Unit& u, int wr, int wc, int fr, int fq) const {
;     ...
;                     a0[0] += ALPHA * bflo(hw.x); a0[1] += ALPHA * bfhi(hw.x); a0[2] += ALPHA * bflo(hw.y); a0[3] += ALPHA * bfhi(hw.y);
;                     a1[0] += ALPHA * bflo(hw.z); a1[1] += ALPHA * bfhi(hw.z); a1[2] += ALPHA * bflo(hw.w); a1[3] += ALPHA * bfhi(hw.w);
;                     *(pg8::f32x4*)(zr + c) = a0; *(pg8::f32x4*)(zr + c + 4) = a1; } }
	v_lshlrev_b32_e32 v222, 16, v212
	v_and_b32_e32 v212, 0xffff0000, v212
	v_fmac_f32_e32 v14, s22, v222
	v_fmac_f32_e32 v15, s22, v212
	v_lshlrev_b32_e32 v223, 16, v213
	v_and_b32_e32 v213, 0xffff0000, v213
	v_fmac_f32_e32 v16, s22, v223
	v_fmac_f32_e32 v17, s22, v213
	v_lshlrev_b32_e32 v222, 16, v214
	v_and_b32_e32 v214, 0xffff0000, v214
	v_fmac_f32_e32 v10, s22, v222
	v_fmac_f32_e32 v11, s22, v214
	v_lshlrev_b32_e32 v223, 16, v215
	v_and_b32_e32 v215, 0xffff0000, v215
	v_fmac_f32_e32 v12, s22, v223
	v_fmac_f32_e32 v13, s22, v215
	s_waitcnt vmcnt(0)
	v_lshlrev_b32_e32 v222, 16, v216
	v_and_b32_e32 v216, 0xffff0000, v216
	v_fmac_f32_e32 v6, s22, v222
	v_fmac_f32_e32 v7, s22, v216
	v_lshlrev_b32_e32 v223, 16, v217
	v_and_b32_e32 v217, 0xffff0000, v217
	v_fmac_f32_e32 v8, s22, v223
	v_fmac_f32_e32 v9, s22, v217
	v_lshlrev_b32_e32 v222, 16, v218
	v_and_b32_e32 v218, 0xffff0000, v218
	v_fmac_f32_e32 v2, s22, v222
	v_fmac_f32_e32 v3, s22, v218
	v_lshlrev_b32_e32 v223, 16, v219
	v_and_b32_e32 v219, 0xffff0000, v219
	v_fmac_f32_e32 v4, s22, v223
	v_fmac_f32_e32 v5, s22, v219
	global_store_dwordx4 v221, v[126:129], s[100:101]
	global_store_dwordx4 v221, v[122:125], s[100:101] offset:16
	global_store_dwordx4 v221, v[118:121], s[100:101] offset:512
	global_store_dwordx4 v221, v[114:117], s[100:101] offset:528
	s_add_u32 s100, s100, 0x20000
	s_addc_u32 s101, s101, 0
	global_store_dwordx4 v221, v[110:113], s[100:101]
	global_store_dwordx4 v221, v[106:109], s[100:101] offset:16
	global_store_dwordx4 v221, v[102:105], s[100:101] offset:512
	global_store_dwordx4 v221, v[98:101], s[100:101] offset:528
	s_add_u32 s100, s100, 0x20000
	s_addc_u32 s101, s101, 0
	global_store_dwordx4 v221, v[94:97], s[100:101]
	global_store_dwordx4 v221, v[90:93], s[100:101] offset:16
	global_store_dwordx4 v221, v[86:89], s[100:101] offset:512
	global_store_dwordx4 v221, v[82:85], s[100:101] offset:528
	s_add_u32 s100, s100, 0x20000
	s_addc_u32 s101, s101, 0
	global_store_dwordx4 v221, v[78:81], s[100:101]
	global_store_dwordx4 v221, v[74:77], s[100:101] offset:16
	global_store_dwordx4 v221, v[70:73], s[100:101] offset:512
	global_store_dwordx4 v221, v[66:69], s[100:101] offset:528
	s_add_u32 s100, s100, 0xa0000
	s_addc_u32 s101, s101, 0
	global_store_dwordx4 v221, v[62:65], s[100:101]
	global_store_dwordx4 v221, v[58:61], s[100:101] offset:16
	global_store_dwordx4 v221, v[54:57], s[100:101] offset:512
	global_store_dwordx4 v221, v[50:53], s[100:101] offset:528
	s_add_u32 s100, s100, 0x20000
	s_addc_u32 s101, s101, 0
	global_store_dwordx4 v221, v[46:49], s[100:101]
	global_store_dwordx4 v221, v[42:45], s[100:101] offset:16
	global_store_dwordx4 v221, v[38:41], s[100:101] offset:512
	global_store_dwordx4 v221, v[34:37], s[100:101] offset:528
	s_add_u32 s100, s100, 0x20000
	s_addc_u32 s101, s101, 0
	global_store_dwordx4 v221, v[30:33], s[100:101]
	global_store_dwordx4 v221, v[26:29], s[100:101] offset:16
	global_store_dwordx4 v221, v[22:25], s[100:101] offset:512
	global_store_dwordx4 v221, v[18:21], s[100:101] offset:528
	s_add_u32 s100, s100, 0x20000
	s_addc_u32 s101, s101, 0
	global_store_dwordx4 v221, v[14:17], s[100:101]
	global_store_dwordx4 v221, v[10:13], s[100:101] offset:16
	global_store_dwordx4 v221, v[6:9], s[100:101] offset:512
	global_store_dwordx4 v221, v[2:5], s[100:101] offset:528
	s_cbranch_vccnz .LBB0_2803
	s_andn2_b64 vcc, exec, s[10:11]
	s_cbranch_vccnz .LBB0_2802
	s_barrier
	s_branch .LBB0_2802

; __global__ void __launch_bounds__(512) hymba_fwd(Params P0) {
;     extern __shared__ __attribute__((aligned(16))) char lds[];
	.amdhsa_kernel _Z9hymba_fwd6Params
		.amdhsa_group_segment_fixed_size 256
		.amdhsa_private_segment_fixed_size 0
		.amdhsa_kernarg_size 416
		.amdhsa_user_sgpr_count 2
		.amdhsa_user_sgpr_dispatch_ptr 0
		.amdhsa_user_sgpr_queue_ptr 0
		.amdhsa_user_sgpr_kernarg_segment_ptr 1
		.amdhsa_user_sgpr_dispatch_id 0
		.amdhsa_user_sgpr_kernarg_preload_length 0
		.amdhsa_user_sgpr_kernarg_preload_offset 0
		.amdhsa_user_sgpr_private_segment_size 0
		.amdhsa_uses_dynamic_stack 0
		.amdhsa_enable_private_segment 0
		.amdhsa_system_sgpr_workgroup_id_x 1
		.amdhsa_system_sgpr_workgroup_id_y 0
		.amdhsa_system_sgpr_workgroup_id_z 0
		.amdhsa_system_sgpr_workgroup_info 0
		.amdhsa_system_vgpr_workitem_id 2
		.amdhsa_next_free_vgpr 251
		.amdhsa_next_free_sgpr 102
		.amdhsa_accum_offset 252
		.amdhsa_reserve_vcc 1
		.amdhsa_float_round_mode_32 0
		.amdhsa_float_round_mode_16_64 0
		.amdhsa_float_denorm_mode_32 3
		.amdhsa_float_denorm_mode_16_64 3
		.amdhsa_dx10_clamp 1
		.amdhsa_ieee_mode 1
		.amdhsa_fp16_overflow 0
		.amdhsa_tg_split 0
		.amdhsa_exception_fp_ieee_invalid_op 0
		.amdhsa_exception_fp_denorm_src 0
		.amdhsa_exception_fp_ieee_div_zero 0
		.amdhsa_exception_fp_ieee_overflow 0
		.amdhsa_exception_fp_ieee_underflow 0
		.amdhsa_exception_fp_ieee_inexact 0
		.amdhsa_exception_int_div_zero 0
	.end_amdhsa_kernel

; __global__ void __launch_bounds__(512) hymba_fwd(Params P0) {
amdhsa.kernels:
  - .agpr_count:     0
    .args:
      - .offset:         0
        .size:           160
        .value_kind:     by_value
      - .offset:         160
        .size:           4
        .value_kind:     hidden_block_count_x
      - .offset:         164
        .size:           4
        .value_kind:     hidden_block_count_y
      - .offset:         168
        .size:           4
        .value_kind:     hidden_block_count_z
      - .offset:         172
        .size:           2
        .value_kind:     hidden_group_size_x
      - .offset:         174
        .size:           2
        .value_kind:     hidden_group_size_y
      - .offset:         176
        .size:           2
        .value_kind:     hidden_group_size_z
      - .offset:         178
        .size:           2
        .value_kind:     hidden_remainder_x
      - .offset:         180
        .size:           2
        .value_kind:     hidden_remainder_y
      - .offset:         182
        .size:           2
        .value_kind:     hidden_remainder_z
      - .offset:         200
        .size:           8
        .value_kind:     hidden_global_offset_x
      - .offset:         208
        .size:           8
        .value_kind:     hidden_global_offset_y
      - .offset:         216
        .size:           8
        .value_kind:     hidden_global_offset_z
      - .offset:         224
        .size:           2
        .value_kind:     hidden_grid_dims
      - .offset:         248
        .size:           8
        .value_kind:     hidden_multigrid_sync_arg
      - .offset:         280
        .size:           4
        .value_kind:     hidden_dynamic_lds_size
    .group_segment_fixed_size: 256
    .kernarg_segment_align: 8
    .kernarg_segment_size: 416
    .language:       OpenCL C
    .language_version:
      - 2
      - 0
    .max_flat_workgroup_size: 512
    .name:           _Z9hymba_fwd6Params
    .private_segment_fixed_size: 0
    .sgpr_count:     108
    .sgpr_spill_count: 28
    .symbol:         _Z9hymba_fwd6Params.kd
    .uniform_work_group_size: 1
    .uses_dynamic_stack: false
    .vgpr_count:     251
    .vgpr_spill_count: 0
    .wavefront_size: 64
